# v6: W1 split + W1 L2 prefetch + batched part loads in cmpwin/sel epilogues
# speedup vs baseline: 1.0367x; 1.0084x over previous
; DI int tidx() { int t = threadIdx.x; asm volatile("" : "+v"(t)); return t; }
; DI f32x4 zero4() { float z0 = 0.f; asm volatile("" : "+v"(z0)); return (f32x4){z0, z0, z0, z0}; }
; DI void gemm_mainloop_deep(const bf16_t* __restrict__ A, int lda, const bf16_t* __restrict__ Bt, int ldb, int K, int m0, int n0,
;                            f32x4 (&acc)[2][8], char* smem, bool prefetched) {
;   const int tid = tidx(), wave = tid >> 6, lane = tid & 63;
;   const bf16_t* ag[4]; const bf16_t* bg[4];
; #pragma unroll
;   for (int i = 0; i < 4; ++i) {
;     const int row = (i * 4 + wave) * 8 + (lane >> 3), chunk = (lane & 7) ^ ((row >> 1) & 7);
;     ag[i] = A + (size_t)(m0 + row) * lda + chunk * 8;
;     bg[i] = Bt + (size_t)(n0 + row) * ldb + chunk * 8;
;   }
;   const int nk = K >> 6;
;     ...
;   const unsigned i16 = lane & 15, gq = lane >> 4, sw = (i16 >> 1) & 7;
;   const unsigned lb = (unsigned)(size_t)smem + i16 * 128;
;   const unsigned o0 = (gq ^ sw) << 4, o1 = ((4 + gq) ^ sw) << 4;
;   bf16x8 af[2][2], bfr[2][8];
;   if (!prefetched) { GSTAGE(0, 0); }
;   asm volatile("s_waitcnt vmcnt(0)" ::: "memory");
;   __syncthreads();
; template <int EPI>
; DI void gemm_phase(const GArgs& g, char* smem) {
;     ...
;     const int m0 = (tile % ntm) * 128, n0 = (tile / ntm) * 128;
;     f32x4 acc[2][8];
; #pragma unroll
;     for (int mi = 0; mi < 2; ++mi)
; #pragma unroll
;       for (int ni = 0; ni < 8; ++ni) acc[mi][ni] = zero4();
.LBB0_348:
	s_ashr_i32 s4, s6, 31
	s_lshr_b32 s4, s4, 28
	s_add_i32 s5, s6, s4
	v_mov_b32_e32 v62, v1
	v_mov_b32_e32 v58, v1
	v_mov_b32_e32 v54, v1
	v_mov_b32_e32 v50, v1
	v_mov_b32_e32 v46, v1
	v_mov_b32_e32 v42, v1
	v_mov_b32_e32 v38, v1
	v_mov_b32_e32 v34, v1
	v_mov_b32_e32 v30, v1
	v_mov_b32_e32 v26, v1
	v_mov_b32_e32 v22, v1
	v_mov_b32_e32 v18, v1
	v_mov_b32_e32 v14, v1
	v_mov_b32_e32 v10, v1
	v_mov_b32_e32 v6, v1
	v_mov_b32_e32 v2, v1
	v_mov_b32_e32 v3, v190
	s_ashr_i32 s4, s5, 4
	s_and_b32 s5, s5, 0x1fffff0
	s_sub_i32 s5, s6, s5
	v_ashrrev_i32_e32 v7, 6, v3
	v_lshlrev_b32_e32 v11, 3, v7
	v_bfe_u32 v15, v3, 3, 3
	s_lshl_b32 s7, s5, 7
	s_lshl_b32 s8, s4, 7
	v_or_b32_e32 v19, v11, v15
	v_lshrrev_b32_e32 v23, 1, v19
	v_add_u32_e32 v4, s7, v19
	v_add_u32_e32 v8, s8, v19
	v_add_u32_e32 v16, 32, v19
	v_add_u32_e32 v24, 64, v19
	v_add_u32_e32 v19, 0x60, v19
	v_xor_b32_e32 v0, v23, v3
	v_ashrrev_i32_e32 v5, 31, v4
	v_readlane_b32 s10, v252, 55
	v_add_u32_e32 v12, s7, v16
	v_add_u32_e32 v20, s7, v24
	v_add_u32_e32 v28, s7, v19
	v_lshlrev_b64 v[4:5], 13, v[4:5]
	v_readlane_b32 s11, v252, 56
	v_lshlrev_b32_e32 v0, 4, v0
	v_ashrrev_i32_e32 v9, 31, v8
	v_ashrrev_i32_e32 v13, 31, v12
	v_ashrrev_i32_e32 v21, 31, v20
	v_ashrrev_i32_e32 v29, 31, v28
	v_add_u32_e32 v32, s8, v19
	v_bfe_u32 v19, v3, 4, 2
	v_bfe_u32 v27, v3, 1, 3
	v_lshlrev_b32_e32 v168, 10, v7
	v_lshl_add_u64 v[4:5], s[10:11], 0, v[4:5]
	v_and_b32_e32 v0, 0x70, v0
	v_lshlrev_b64 v[8:9], 13, v[8:9]
	v_lshlrev_b64 v[12:13], 13, v[12:13]
	v_lshlrev_b64 v[20:21], 13, v[20:21]
	v_lshlrev_b64 v[28:29], 13, v[28:29]
	v_xor_b32_e32 v31, v19, v27
	v_bitop3_b32 v19, v19, v27, 4 bitop3:0x36
	v_add_u32_e32 v27, 0x8000, v168
	v_lshl_add_u64 v[4:5], v[4:5], 0, v[0:1]
	v_lshl_add_u64 v[8:9], s[0:1], 0, v[8:9]
	v_lshl_add_u64 v[12:13], s[10:11], 0, v[12:13]
	v_lshl_add_u64 v[20:21], s[10:11], 0, v[20:21]
	v_lshl_add_u64 v[28:29], s[10:11], 0, v[28:29]
	s_mov_b64 s[10:11], 0x80
	v_readfirstlane_b32 s5, v27
	v_lshl_add_u64 v[8:9], v[8:9], 0, v[0:1]
	v_add_u32_e32 v16, s8, v16
	v_lshl_add_u64 v[4:5], v[4:5], 0, s[10:11]
	s_mov_b32 m0, s5
	v_ashrrev_i32_e32 v17, 31, v16
	s_waitcnt vmcnt(0)
	s_waitcnt vmcnt(0) lgkmcnt(0)
	s_barrier
; DI int tidx() { int t = threadIdx.x; asm volatile("" : "+v"(t)); return t; }
; DI void gemm_mainloop_deep(const bf16_t* __restrict__ A, int lda, const bf16_t* __restrict__ Bt, int ldb, int K, int m0, int n0,
;                            f32x4 (&acc)[2][8], char* smem, bool prefetched) {
;   const int tid = tidx(), wave = tid >> 6, lane = tid & 63;
;   const bf16_t* ag[4]; const bf16_t* bg[4];
; #pragma unroll
;   for (int i = 0; i < 4; ++i) {
;     const int row = (i * 4 + wave) * 8 + (lane >> 3), chunk = (lane & 7) ^ ((row >> 1) & 7);
;     ag[i] = A + (size_t)(m0 + row) * lda + chunk * 8;
;     bg[i] = Bt + (size_t)(n0 + row) * ldb + chunk * 8;
;   }
;   const int nk = K >> 6;
;     ...
;   const unsigned i16 = lane & 15, gq = lane >> 4, sw = (i16 >> 1) & 7;
;   const unsigned lb = (unsigned)(size_t)smem + i16 * 128;
;   const unsigned o0 = (gq ^ sw) << 4, o1 = ((4 + gq) ^ sw) << 4;
;   bf16x8 af[2][2], bfr[2][8];
;   if (!prefetched) { GSTAGE(0, 0); }
;   asm volatile("s_waitcnt vmcnt(0)" ::: "memory");
;   __syncthreads();
;   if (nk > 1) { GSTAGE(1, 1); }
;   { const unsigned a = lb + wave * 4096 + o0, b = lb + 16384 + o0; RDSET(0, a, b); }
	global_load_lds_dwordx4 v[4:5], off
	v_lshl_add_u64 v[4:5], v[8:9], 0, s[10:11]
	v_add_u32_e32 v8, 0xc000, v168
	v_lshlrev_b64 v[16:17], 13, v[16:17]
	v_add_u32_e32 v24, s8, v24
	v_readfirstlane_b32 s5, v8
	v_add_u32_e32 v8, 0x9000, v168
	v_lshl_add_u64 v[12:13], v[12:13], 0, v[0:1]
	v_lshl_add_u64 v[16:17], s[0:1], 0, v[16:17]
	v_ashrrev_i32_e32 v25, 31, v24
	s_mov_b32 m0, s5
	v_readfirstlane_b32 s5, v8
	v_add_u32_e32 v8, 0xd000, v168
	v_lshl_add_u64 v[16:17], v[16:17], 0, v[0:1]
	v_lshlrev_b64 v[24:25], 13, v[24:25]
	global_load_lds_dwordx4 v[4:5], off
	v_lshl_add_u64 v[4:5], v[12:13], 0, s[10:11]
	s_mov_b32 m0, s5
	v_readfirstlane_b32 s5, v8
	v_add_u32_e32 v8, 0xa000, v168
	v_lshl_add_u64 v[20:21], v[20:21], 0, v[0:1]
	v_lshl_add_u64 v[24:25], s[0:1], 0, v[24:25]
	v_ashrrev_i32_e32 v33, 31, v32
	global_load_lds_dwordx4 v[4:5], off
	v_lshl_add_u64 v[4:5], v[16:17], 0, s[10:11]
	s_mov_b32 m0, s5
	v_readfirstlane_b32 s5, v8
	v_add_u32_e32 v8, 0xe000, v168
	v_lshl_add_u64 v[24:25], v[24:25], 0, v[0:1]
	v_lshlrev_b64 v[32:33], 13, v[32:33]
	global_load_lds_dwordx4 v[4:5], off
	v_lshl_add_u64 v[4:5], v[20:21], 0, s[10:11]
	s_mov_b32 m0, s5
	v_readfirstlane_b32 s5, v8
	v_add_u32_e32 v8, 0xb000, v168
	v_lshl_add_u64 v[28:29], v[28:29], 0, v[0:1]
	v_lshl_add_u64 v[32:33], s[0:1], 0, v[32:33]
	global_load_lds_dwordx4 v[4:5], off
	v_lshl_add_u64 v[4:5], v[24:25], 0, s[10:11]
	s_mov_b32 m0, s5
	v_readfirstlane_b32 s5, v8
	v_add_u32_e32 v8, 0xf000, v168
	v_lshl_add_u64 v[32:33], v[32:33], 0, v[0:1]
	global_load_lds_dwordx4 v[4:5], off
	v_lshl_add_u64 v[4:5], v[28:29], 0, s[10:11]
	s_mov_b32 m0, s5
	v_readfirstlane_b32 s5, v8
	global_load_lds_dwordx4 v[4:5], off
	v_lshl_add_u64 v[4:5], v[32:33], 0, s[10:11]
	s_mov_b32 m0, s5
	v_and_b32_e32 v0, 15, v3
	global_load_lds_dwordx4 v[4:5], off
	v_lshlrev_b32_e32 v31, 4, v31
	v_lshlrev_b32_e32 v4, 12, v7
	v_lshlrev_b32_e32 v0, 7, v0
	v_or_b32_e32 v169, v31, v4
	v_or_b32_e32 v5, v169, v0
	ds_read_b128 v[66:69], v5 offset:0
	v_or_b32_e32 v170, 0x4000, v31
	ds_read_b128 v[70:73], v5 offset:0x800
	v_or_b32_e32 v7, v170, v0
	ds_read_b128 v[74:77], v7 offset:0
	ds_read_b128 v[78:81], v7 offset:0x800
	ds_read_b128 v[82:85], v7 offset:0x1000
	ds_read_b128 v[86:89], v7 offset:0x1800
	ds_read_b128 v[90:93], v7 offset:0x2000
	ds_read_b128 v[94:97], v7 offset:0x2800
	ds_read_b128 v[98:101], v7 offset:0x3000
	v_lshlrev_b32_e32 v19, 4, v19
	ds_read_b128 v[102:105], v7 offset:0x3800
	v_or_b32_e32 v7, 0x60, v15
	v_or_b32_e32 v171, v19, v4
	v_or_b32_e32 v4, s8, v7
	v_add_u32_e32 v4, v4, v11
	v_ashrrev_i32_e32 v5, 31, v4
	v_bitop3_b32 v3, v23, 7, v3 bitop3:0x48
	v_lshlrev_b64 v[4:5], 13, v[4:5]
	v_lshlrev_b32_e32 v3, 4, v3
	v_or_b32_e32 v4, v4, v3
	s_lshl_b32 s5, s6, 7
	v_lshl_add_u64 v[146:147], s[2:3], 0, v[4:5]
	v_or_b32_e32 v4, s5, v7
	v_add_u32_e32 v4, v4, v11
	s_lshl_b32 s4, s4, 11
	v_subrev_u32_e32 v4, s4, v4
	v_ashrrev_i32_e32 v5, 31, v4
	v_lshlrev_b64 v[4:5], 13, v[4:5]
	v_readlane_b32 s10, v253, 40
	v_or_b32_e32 v4, v4, v3
	v_readlane_b32 s11, v253, 41
	v_or_b32_e32 v7, 64, v15
	s_mov_b32 s9, 0
	v_lshl_add_u64 v[152:153], s[10:11], 0, v[4:5]
	v_or_b32_e32 v4, s8, v7
	v_add_u32_e32 v4, v4, v11
	v_ashrrev_i32_e32 v5, 31, v4
	v_lshlrev_b64 v[4:5], 13, v[4:5]
	v_or_b32_e32 v4, v4, v3
	v_lshl_add_u64 v[154:155], s[2:3], 0, v[4:5]
	v_or_b32_e32 v4, s5, v7
	v_add_u32_e32 v4, v4, v11
	v_subrev_u32_e32 v4, s4, v4
	v_ashrrev_i32_e32 v5, 31, v4
	v_lshlrev_b64 v[4:5], 13, v[4:5]
	v_or_b32_e32 v4, v4, v3
	v_or_b32_e32 v7, 32, v15
	v_lshl_add_u64 v[156:157], s[10:11], 0, v[4:5]
	v_or_b32_e32 v4, s8, v7
	v_add_u32_e32 v4, v4, v11
	v_ashrrev_i32_e32 v5, 31, v4
	v_lshlrev_b64 v[4:5], 13, v[4:5]
	v_or_b32_e32 v4, v4, v3
	v_lshl_add_u64 v[158:159], s[2:3], 0, v[4:5]
	v_or_b32_e32 v4, s5, v7
	v_add_u32_e32 v4, v4, v11
	v_subrev_u32_e32 v4, s4, v4
	v_ashrrev_i32_e32 v5, 31, v4
	v_lshlrev_b64 v[4:5], 13, v[4:5]
	v_or_b32_e32 v4, v4, v3
	v_lshl_add_u64 v[160:161], s[10:11], 0, v[4:5]
	v_or_b32_e32 v4, s8, v15
	v_add_u32_e32 v4, v4, v11
	v_ashrrev_i32_e32 v5, 31, v4
	v_lshlrev_b64 v[4:5], 13, v[4:5]
	v_or_b32_e32 v4, v4, v3
	v_lshl_add_u64 v[162:163], s[2:3], 0, v[4:5]
	v_or_b32_e32 v4, s5, v15
	v_add_u32_e32 v4, v4, v11
	v_subrev_u32_e32 v4, s4, v4
	v_ashrrev_i32_e32 v5, 31, v4
	v_lshlrev_b64 v[4:5], 13, v[4:5]
	v_or_b32_e32 v4, v4, v3
	v_or_b32_e32 v172, 0x4000, v19
	v_lshl_add_u64 v[164:165], s[10:11], 0, v[4:5]
	v_and_b32_e32 v177, 7, v190
	v_mov_b32_e32 v178, v164
	v_mov_b32_e32 v179, v165
	v_cmp_eq_u32_e64 s[100:101], 1, v177
	s_nop 1
	v_cndmask_b32_e64 v178, v178, v162, s[100:101]
	v_cndmask_b32_e64 v179, v179, v163, s[100:101]
	v_cmp_eq_u32_e64 s[100:101], 2, v177
	s_nop 1
	v_cndmask_b32_e64 v178, v178, v160, s[100:101]
	v_cndmask_b32_e64 v179, v179, v161, s[100:101]
	v_cmp_eq_u32_e64 s[100:101], 3, v177
	s_nop 1
	v_cndmask_b32_e64 v178, v178, v158, s[100:101]
	v_cndmask_b32_e64 v179, v179, v159, s[100:101]
	v_cmp_eq_u32_e64 s[100:101], 4, v177
	s_nop 1
	v_cndmask_b32_e64 v178, v178, v156, s[100:101]
	v_cndmask_b32_e64 v179, v179, v157, s[100:101]
	v_cmp_eq_u32_e64 s[100:101], 5, v177
	s_nop 1
	v_cndmask_b32_e64 v178, v178, v154, s[100:101]
	v_cndmask_b32_e64 v179, v179, v155, s[100:101]
	v_cmp_eq_u32_e64 s[100:101], 6, v177
	s_nop 1
	v_cndmask_b32_e64 v178, v178, v152, s[100:101]
	v_cndmask_b32_e64 v179, v179, v153, s[100:101]
	v_cmp_eq_u32_e64 s[100:101], 7, v177
	s_nop 1
	v_cndmask_b32_e64 v178, v178, v146, s[100:101]
	v_cndmask_b32_e64 v179, v179, v147, s[100:101]
	s_nop 0
	global_load_dword v177, v[178:179], off offset:0 sc1
	s_mov_b64 s[4:5], 0
	s_mov_b32 s10, 0
	v_mov_b32_e32 v3, v2
	v_mov_b32_e32 v4, v2
	v_mov_b32_e32 v5, v2
	v_mov_b32_e32 v7, v6
	v_mov_b32_e32 v8, v6
	v_mov_b32_e32 v9, v6
	v_mov_b32_e32 v11, v10
	v_mov_b32_e32 v12, v10
	v_mov_b32_e32 v13, v10
	v_mov_b32_e32 v15, v14
	v_mov_b32_e32 v16, v14
	v_mov_b32_e32 v17, v14
	v_mov_b32_e32 v19, v18
	v_mov_b32_e32 v20, v18
	v_mov_b32_e32 v21, v18
	v_mov_b32_e32 v23, v22
	v_mov_b32_e32 v24, v22
	v_mov_b32_e32 v25, v22
	v_mov_b32_e32 v27, v26
	v_mov_b32_e32 v28, v26
	v_mov_b32_e32 v29, v26
	v_mov_b32_e32 v31, v30
	v_mov_b32_e32 v32, v30
	v_mov_b32_e32 v33, v30
	v_mov_b32_e32 v35, v34
	v_mov_b32_e32 v36, v34
	v_mov_b32_e32 v37, v34
	v_mov_b32_e32 v39, v38
	v_mov_b32_e32 v40, v38
	v_mov_b32_e32 v41, v38
	v_mov_b32_e32 v43, v42
	v_mov_b32_e32 v44, v42
	v_mov_b32_e32 v45, v42
	v_mov_b32_e32 v47, v46
	v_mov_b32_e32 v48, v46
	v_mov_b32_e32 v49, v46
	v_mov_b32_e32 v51, v50
	v_mov_b32_e32 v52, v50
	v_mov_b32_e32 v53, v50
	v_mov_b32_e32 v55, v54
	v_mov_b32_e32 v56, v54
	v_mov_b32_e32 v57, v54
	v_mov_b32_e32 v59, v58
	v_mov_b32_e32 v60, v58
	v_mov_b32_e32 v61, v58
	v_mov_b32_e32 v63, v62
	v_mov_b32_e32 v64, v62
	v_mov_b32_e32 v65, v62
	s_branch .LBB0_350

; #define MMSET(S)                                                                                                          \
;   _Pragma("unroll") for (int mi = 0; mi < 2; ++mi)                                                                        \
;   _Pragma("unroll") for (int ni = 0; ni < 8; ++ni) acc[mi][ni] = __builtin_amdgcn_mfma_f32_16x16x32_bf16(bfr[S][ni], af[S][mi], acc[mi][ni], 0, 0, 0);
; DI void gemm_mainloop_deep(const bf16_t* __restrict__ A, int lda, const bf16_t* __restrict__ Bt, int ldb, int K, int m0, int n0,
;                            f32x4 (&acc)[2][8], char* smem, bool prefetched) {
;     ...
;   for (int kt = 0; kt < nk; ++kt) {
;     const unsigned cb = lb + (kt & 1) * 32768, nb = lb + ((kt & 1) ^ 1) * 32768;
;     { const unsigned a = cb + wave * 4096 + o1, b = cb + 16384 + o1; RDSET(1, a, b); }
;     __builtin_amdgcn_sched_barrier(0);
;     asm volatile("s_waitcnt lgkmcnt(10)" ::: "memory");
;     __builtin_amdgcn_sched_barrier(0);
;     MMSET(0)
;     __builtin_amdgcn_sched_barrier(0);
;     asm volatile("s_waitcnt lgkmcnt(0)\n\ts_waitcnt vmcnt(0)" ::: "memory");
;     __syncthreads();
;     __builtin_amdgcn_sched_barrier(0);
;     if (kt + 2 < nk) { GSTAGE(kt & 1, kt + 2); }
.LBB0_350:
	s_and_b32 s11, s9, 0x8000
	v_or_b32_e32 v106, s11, v0
	v_add_u32_e32 v107, v106, v171
	ds_read_b128 v[110:113], v107 offset:0
	v_add_u32_e32 v142, v106, v172
	ds_read_b128 v[106:109], v107 offset:0x800
	ds_read_b128 v[114:117], v142 offset:0
	ds_read_b128 v[118:121], v142 offset:0x800
	ds_read_b128 v[122:125], v142 offset:0x1000
	ds_read_b128 v[126:129], v142 offset:0x1800
	ds_read_b128 v[130:133], v142 offset:0x2000
	ds_read_b128 v[134:137], v142 offset:0x2800
	ds_read_b128 v[138:141], v142 offset:0x3000
	ds_read_b128 v[142:145], v142 offset:0x3800
	s_waitcnt lgkmcnt(10)
	v_mfma_f32_16x16x32_bf16 v[62:65], v[74:77], v[66:69], v[62:65]
	v_mfma_f32_16x16x32_bf16 v[58:61], v[78:81], v[66:69], v[58:61]
	v_mfma_f32_16x16x32_bf16 v[54:57], v[82:85], v[66:69], v[54:57]
	v_mfma_f32_16x16x32_bf16 v[50:53], v[86:89], v[66:69], v[50:53]
	v_mfma_f32_16x16x32_bf16 v[46:49], v[90:93], v[66:69], v[46:49]
	v_mfma_f32_16x16x32_bf16 v[42:45], v[94:97], v[66:69], v[42:45]
	v_mfma_f32_16x16x32_bf16 v[38:41], v[98:101], v[66:69], v[38:41]
	v_mfma_f32_16x16x32_bf16 v[34:37], v[102:105], v[66:69], v[34:37]
	v_mfma_f32_16x16x32_bf16 v[30:33], v[74:77], v[70:73], v[30:33]
	v_mfma_f32_16x16x32_bf16 v[26:29], v[78:81], v[70:73], v[26:29]
	v_mfma_f32_16x16x32_bf16 v[22:25], v[82:85], v[70:73], v[22:25]
	v_mfma_f32_16x16x32_bf16 v[18:21], v[86:89], v[70:73], v[18:21]
	v_mfma_f32_16x16x32_bf16 v[14:17], v[90:93], v[70:73], v[14:17]
	v_mfma_f32_16x16x32_bf16 v[10:13], v[94:97], v[70:73], v[10:13]
	v_mfma_f32_16x16x32_bf16 v[6:9], v[98:101], v[70:73], v[6:9]
	v_mfma_f32_16x16x32_bf16 v[2:5], v[102:105], v[70:73], v[2:5]
	s_waitcnt lgkmcnt(0)
	s_waitcnt vmcnt(1)
	s_waitcnt vmcnt(1) lgkmcnt(0)
	s_barrier
	s_cmp_gt_u32 s10, 61
	s_cbranch_scc1 .LBB0_352
	v_add_u32_e32 v173, s11, v168
	v_add_u32_e32 v176, 0x4000, v173
	v_readfirstlane_b32 s12, v173
	v_lshl_add_u64 v[174:175], v[164:165], 0, s[4:5]
	s_mov_b32 m0, s12
	v_readfirstlane_b32 s12, v176
	v_add_u32_e32 v176, 0x1000, v173
	global_load_lds_dwordx4 v[174:175], off
	v_lshl_add_u64 v[174:175], v[162:163], 0, s[4:5]
	s_mov_b32 m0, s12
	v_readfirstlane_b32 s12, v176
	v_add_u32_e32 v176, 0x5000, v173
	global_load_lds_dwordx4 v[174:175], off
	v_lshl_add_u64 v[174:175], v[160:161], 0, s[4:5]
	s_mov_b32 m0, s12
	v_readfirstlane_b32 s12, v176
	v_add_u32_e32 v176, 0x2000, v173
	global_load_lds_dwordx4 v[174:175], off
	v_lshl_add_u64 v[174:175], v[158:159], 0, s[4:5]
	s_mov_b32 m0, s12
	v_readfirstlane_b32 s12, v176
	v_add_u32_e32 v176, 0x6000, v173
	global_load_lds_dwordx4 v[174:175], off
	v_lshl_add_u64 v[174:175], v[156:157], 0, s[4:5]
	s_mov_b32 m0, s12
	v_readfirstlane_b32 s12, v176
	v_add_u32_e32 v176, 0x3000, v173
	global_load_lds_dwordx4 v[174:175], off
	v_lshl_add_u64 v[174:175], v[154:155], 0, s[4:5]
	s_mov_b32 m0, s12
	v_readfirstlane_b32 s12, v176
	v_add_u32_e32 v173, 0x7000, v173
	global_load_lds_dwordx4 v[174:175], off
	v_lshl_add_u64 v[174:175], v[152:153], 0, s[4:5]
	s_mov_b32 m0, s12
	v_readfirstlane_b32 s12, v173
	global_load_lds_dwordx4 v[174:175], off
	v_lshl_add_u64 v[174:175], v[146:147], 0, s[4:5]
	s_mov_b32 m0, s12
	s_nop 0
	global_load_lds_dwordx4 v[174:175], off
	v_lshl_add_u64 v[180:181], v[178:179], 0, s[4:5]
	global_load_dword v177, v[180:181], off offset:128 sc1

; DI int tidx() { int t = threadIdx.x; asm volatile("" : "+v"(t)); return t; }
; DI f32x4 zero4() { float z0 = 0.f; asm volatile("" : "+v"(z0)); return (f32x4){z0, z0, z0, z0}; }
; DI void gemm_mainloop_deep(const bf16_t* __restrict__ A, int lda, const bf16_t* __restrict__ Bt, int ldb, int K, int m0, int n0,
;                            f32x4 (&acc)[2][8], char* smem, bool prefetched) {
;   const int tid = tidx(), wave = tid >> 6, lane = tid & 63;
;   const bf16_t* ag[4]; const bf16_t* bg[4];
; #pragma unroll
;   for (int i = 0; i < 4; ++i) {
;     const int row = (i * 4 + wave) * 8 + (lane >> 3), chunk = (lane & 7) ^ ((row >> 1) & 7);
;     ag[i] = A + (size_t)(m0 + row) * lda + chunk * 8;
;     bg[i] = Bt + (size_t)(n0 + row) * ldb + chunk * 8;
;   }
;   const int nk = K >> 6;
;     ...
;   const unsigned i16 = lane & 15, gq = lane >> 4, sw = (i16 >> 1) & 7;
;   const unsigned lb = (unsigned)(size_t)smem + i16 * 128;
;   const unsigned o0 = (gq ^ sw) << 4, o1 = ((4 + gq) ^ sw) << 4;
;   bf16x8 af[2][2], bfr[2][8];
;   if (!prefetched) { GSTAGE(0, 0); }
;   asm volatile("s_waitcnt vmcnt(0)" ::: "memory");
;   __syncthreads();
; template <int EPI>
; DI void gemm_phase(const GArgs& g, char* smem) {
;     ...
;     const int m0 = (tile % ntm) * 128, n0 = (tile / ntm) * 128;
;     f32x4 acc[2][8];
; #pragma unroll
;     for (int mi = 0; mi < 2; ++mi)
; #pragma unroll
;       for (int ni = 0; ni < 8; ++ni) acc[mi][ni] = zero4();
.LBB0_359:
	s_ashr_i32 s2, s4, 31
	s_lshr_b32 s2, s2, 28
	s_add_i32 s3, s4, s2
	v_mov_b32_e32 v62, v1
	v_mov_b32_e32 v58, v1
	v_mov_b32_e32 v54, v1
	v_mov_b32_e32 v50, v1
	v_mov_b32_e32 v46, v1
	v_mov_b32_e32 v42, v1
	v_mov_b32_e32 v38, v1
	v_mov_b32_e32 v34, v1
	v_mov_b32_e32 v30, v1
	v_mov_b32_e32 v26, v1
	v_mov_b32_e32 v22, v1
	v_mov_b32_e32 v18, v1
	v_mov_b32_e32 v14, v1
	v_mov_b32_e32 v10, v1
	v_mov_b32_e32 v6, v1
	v_mov_b32_e32 v2, v1
	v_mov_b32_e32 v3, v190
	s_ashr_i32 s2, s3, 4
	s_and_b32 s3, s3, 0x1fffff0
	s_sub_i32 s3, s4, s3
	v_ashrrev_i32_e32 v7, 6, v3
	v_lshlrev_b32_e32 v11, 3, v7
	v_bfe_u32 v15, v3, 3, 3
	s_lshl_b32 s5, s3, 7
	s_lshl_b32 s6, s2, 7
	v_or_b32_e32 v19, v11, v15
	v_lshrrev_b32_e32 v23, 1, v19
	v_add_u32_e32 v4, s5, v19
	v_add_u32_e32 v8, s6, v19
	v_add_u32_e32 v16, 32, v19
	v_add_u32_e32 v24, 64, v19
	v_add_u32_e32 v19, 0x60, v19
	v_xor_b32_e32 v0, v23, v3
	v_ashrrev_i32_e32 v5, 31, v4
	v_readlane_b32 s8, v252, 57
	v_add_u32_e32 v12, s5, v16
	v_add_u32_e32 v20, s5, v24
	v_add_u32_e32 v28, s5, v19
	v_lshlrev_b64 v[4:5], 13, v[4:5]
	v_readlane_b32 s9, v252, 58
	v_lshlrev_b32_e32 v0, 4, v0
	v_ashrrev_i32_e32 v9, 31, v8
	v_ashrrev_i32_e32 v13, 31, v12
	v_ashrrev_i32_e32 v21, 31, v20
	v_ashrrev_i32_e32 v29, 31, v28
	v_add_u32_e32 v32, s6, v19
	v_bfe_u32 v19, v3, 4, 2
	v_bfe_u32 v27, v3, 1, 3
	v_lshlrev_b32_e32 v168, 10, v7
	v_lshl_add_u64 v[4:5], s[8:9], 0, v[4:5]
	v_and_b32_e32 v0, 0x70, v0
	v_lshlrev_b64 v[8:9], 13, v[8:9]
	v_lshlrev_b64 v[12:13], 13, v[12:13]
	v_lshlrev_b64 v[20:21], 13, v[20:21]
	v_lshlrev_b64 v[28:29], 13, v[28:29]
	v_xor_b32_e32 v31, v19, v27
	v_bitop3_b32 v19, v19, v27, 4 bitop3:0x36
	v_add_u32_e32 v27, 0x8000, v168
	v_lshl_add_u64 v[4:5], v[4:5], 0, v[0:1]
	v_lshl_add_u64 v[8:9], s[0:1], 0, v[8:9]
	v_lshl_add_u64 v[12:13], s[8:9], 0, v[12:13]
	v_lshl_add_u64 v[20:21], s[8:9], 0, v[20:21]
	v_lshl_add_u64 v[28:29], s[8:9], 0, v[28:29]
	s_mov_b64 s[8:9], 0x80
	v_readfirstlane_b32 s3, v27
	v_lshl_add_u64 v[8:9], v[8:9], 0, v[0:1]
	v_add_u32_e32 v16, s6, v16
	v_lshl_add_u64 v[4:5], v[4:5], 0, s[8:9]
	s_mov_b32 m0, s3
	v_ashrrev_i32_e32 v17, 31, v16
	s_waitcnt vmcnt(0)
	s_waitcnt vmcnt(0) lgkmcnt(0)
	s_barrier
; DI int tidx() { int t = threadIdx.x; asm volatile("" : "+v"(t)); return t; }
; DI void gemm_mainloop_deep(const bf16_t* __restrict__ A, int lda, const bf16_t* __restrict__ Bt, int ldb, int K, int m0, int n0,
;                            f32x4 (&acc)[2][8], char* smem, bool prefetched) {
;   const int tid = tidx(), wave = tid >> 6, lane = tid & 63;
;   const bf16_t* ag[4]; const bf16_t* bg[4];
; #pragma unroll
;   for (int i = 0; i < 4; ++i) {
;     const int row = (i * 4 + wave) * 8 + (lane >> 3), chunk = (lane & 7) ^ ((row >> 1) & 7);
;     ag[i] = A + (size_t)(m0 + row) * lda + chunk * 8;
;     bg[i] = Bt + (size_t)(n0 + row) * ldb + chunk * 8;
;   }
;   const int nk = K >> 6;
;     ...
;   const unsigned i16 = lane & 15, gq = lane >> 4, sw = (i16 >> 1) & 7;
;   const unsigned lb = (unsigned)(size_t)smem + i16 * 128;
;   const unsigned o0 = (gq ^ sw) << 4, o1 = ((4 + gq) ^ sw) << 4;
;   bf16x8 af[2][2], bfr[2][8];
;   if (!prefetched) { GSTAGE(0, 0); }
;   asm volatile("s_waitcnt vmcnt(0)" ::: "memory");
;   __syncthreads();
;   if (nk > 1) { GSTAGE(1, 1); }
;   { const unsigned a = lb + wave * 4096 + o0, b = lb + 16384 + o0; RDSET(0, a, b); }
	global_load_lds_dwordx4 v[4:5], off
	v_lshl_add_u64 v[4:5], v[8:9], 0, s[8:9]
	v_add_u32_e32 v8, 0xc000, v168
	v_lshlrev_b64 v[16:17], 13, v[16:17]
	v_add_u32_e32 v24, s6, v24
	v_readfirstlane_b32 s3, v8
	v_add_u32_e32 v8, 0x9000, v168
	v_lshl_add_u64 v[12:13], v[12:13], 0, v[0:1]
	v_lshl_add_u64 v[16:17], s[0:1], 0, v[16:17]
	v_ashrrev_i32_e32 v25, 31, v24
	s_mov_b32 m0, s3
	v_readfirstlane_b32 s3, v8
	v_add_u32_e32 v8, 0xd000, v168
	v_lshl_add_u64 v[16:17], v[16:17], 0, v[0:1]
	v_lshlrev_b64 v[24:25], 13, v[24:25]
	global_load_lds_dwordx4 v[4:5], off
	v_lshl_add_u64 v[4:5], v[12:13], 0, s[8:9]
	s_mov_b32 m0, s3
	v_readfirstlane_b32 s3, v8
	v_add_u32_e32 v8, 0xa000, v168
	v_lshl_add_u64 v[20:21], v[20:21], 0, v[0:1]
	v_lshl_add_u64 v[24:25], s[0:1], 0, v[24:25]
	v_ashrrev_i32_e32 v33, 31, v32
	global_load_lds_dwordx4 v[4:5], off
	v_lshl_add_u64 v[4:5], v[16:17], 0, s[8:9]
	s_mov_b32 m0, s3
	v_readfirstlane_b32 s3, v8
	v_add_u32_e32 v8, 0xe000, v168
	v_lshl_add_u64 v[24:25], v[24:25], 0, v[0:1]
	v_lshlrev_b64 v[32:33], 13, v[32:33]
	global_load_lds_dwordx4 v[4:5], off
	v_lshl_add_u64 v[4:5], v[20:21], 0, s[8:9]
	s_mov_b32 m0, s3
	v_readfirstlane_b32 s3, v8
	v_add_u32_e32 v8, 0xb000, v168
	v_lshl_add_u64 v[28:29], v[28:29], 0, v[0:1]
	v_lshl_add_u64 v[32:33], s[0:1], 0, v[32:33]
	global_load_lds_dwordx4 v[4:5], off
	v_lshl_add_u64 v[4:5], v[24:25], 0, s[8:9]
	s_mov_b32 m0, s3
	v_readfirstlane_b32 s3, v8
	v_add_u32_e32 v8, 0xf000, v168
	v_lshl_add_u64 v[32:33], v[32:33], 0, v[0:1]
	global_load_lds_dwordx4 v[4:5], off
	v_lshl_add_u64 v[4:5], v[28:29], 0, s[8:9]
	s_mov_b32 m0, s3
	v_readfirstlane_b32 s3, v8
	global_load_lds_dwordx4 v[4:5], off
	v_lshl_add_u64 v[4:5], v[32:33], 0, s[8:9]
	s_mov_b32 m0, s3
	v_and_b32_e32 v0, 15, v3
	global_load_lds_dwordx4 v[4:5], off
	v_lshlrev_b32_e32 v31, 4, v31
	v_lshlrev_b32_e32 v4, 12, v7
	v_lshlrev_b32_e32 v0, 7, v0
	v_or_b32_e32 v169, v31, v4
	v_or_b32_e32 v5, v169, v0
	ds_read_b128 v[66:69], v5 offset:0
	v_or_b32_e32 v170, 0x4000, v31
	ds_read_b128 v[70:73], v5 offset:0x800
	v_or_b32_e32 v7, v170, v0
	ds_read_b128 v[74:77], v7 offset:0
	ds_read_b128 v[78:81], v7 offset:0x800
	ds_read_b128 v[82:85], v7 offset:0x1000
	ds_read_b128 v[86:89], v7 offset:0x1800
	ds_read_b128 v[90:93], v7 offset:0x2000
	ds_read_b128 v[94:97], v7 offset:0x2800
	ds_read_b128 v[98:101], v7 offset:0x3000
	v_lshlrev_b32_e32 v19, 4, v19
	ds_read_b128 v[102:105], v7 offset:0x3800
	v_or_b32_e32 v7, 0x60, v15
	v_or_b32_e32 v171, v19, v4
	v_or_b32_e32 v4, s6, v7
	v_add_u32_e32 v4, v4, v11
	v_ashrrev_i32_e32 v5, 31, v4
	v_bitop3_b32 v3, v23, 7, v3 bitop3:0x48
	v_lshlrev_b64 v[4:5], 13, v[4:5]
	v_lshlrev_b32_e32 v3, 4, v3
	v_readlane_b32 s10, v254, 32
	v_or_b32_e32 v4, v4, v3
	v_readlane_b32 s11, v254, 33
	s_lshl_b32 s3, s4, 7
	s_lshl_b32 s2, s2, 11
	v_lshl_add_u64 v[146:147], s[10:11], 0, v[4:5]
	v_or_b32_e32 v4, s3, v7
	v_add_u32_e32 v4, v4, v11
	v_subrev_u32_e32 v4, s2, v4
	v_ashrrev_i32_e32 v5, 31, v4
	v_lshlrev_b64 v[4:5], 13, v[4:5]
	v_readlane_b32 s8, v253, 42
	v_or_b32_e32 v4, v4, v3
	v_readlane_b32 s9, v253, 43
	v_or_b32_e32 v7, 64, v15
	s_mov_b32 s7, 0
	v_lshl_add_u64 v[152:153], s[8:9], 0, v[4:5]
	v_or_b32_e32 v4, s6, v7
	v_add_u32_e32 v4, v4, v11
	v_ashrrev_i32_e32 v5, 31, v4
	v_lshlrev_b64 v[4:5], 13, v[4:5]
	v_or_b32_e32 v4, v4, v3
	v_lshl_add_u64 v[154:155], s[10:11], 0, v[4:5]
	v_or_b32_e32 v4, s3, v7
	v_add_u32_e32 v4, v4, v11
	v_subrev_u32_e32 v4, s2, v4
	v_ashrrev_i32_e32 v5, 31, v4
	v_lshlrev_b64 v[4:5], 13, v[4:5]
	v_or_b32_e32 v4, v4, v3
	v_or_b32_e32 v7, 32, v15
	v_lshl_add_u64 v[156:157], s[8:9], 0, v[4:5]
	v_or_b32_e32 v4, s6, v7
	v_add_u32_e32 v4, v4, v11
	v_ashrrev_i32_e32 v5, 31, v4
	v_lshlrev_b64 v[4:5], 13, v[4:5]
	v_or_b32_e32 v4, v4, v3
	v_lshl_add_u64 v[158:159], s[10:11], 0, v[4:5]
	v_or_b32_e32 v4, s3, v7
	v_add_u32_e32 v4, v4, v11
	v_subrev_u32_e32 v4, s2, v4
	v_ashrrev_i32_e32 v5, 31, v4
	v_lshlrev_b64 v[4:5], 13, v[4:5]
	v_or_b32_e32 v4, v4, v3
	v_lshl_add_u64 v[160:161], s[8:9], 0, v[4:5]
	v_or_b32_e32 v4, s6, v15
	v_add_u32_e32 v4, v4, v11
	v_ashrrev_i32_e32 v5, 31, v4
	v_lshlrev_b64 v[4:5], 13, v[4:5]
	v_or_b32_e32 v4, v4, v3
	v_lshl_add_u64 v[162:163], s[10:11], 0, v[4:5]
	v_or_b32_e32 v4, s3, v15
	v_add_u32_e32 v4, v4, v11
	v_subrev_u32_e32 v4, s2, v4
	v_ashrrev_i32_e32 v5, 31, v4
	v_lshlrev_b64 v[4:5], 13, v[4:5]
	v_or_b32_e32 v4, v4, v3
	v_or_b32_e32 v172, 0x4000, v19
	v_lshl_add_u64 v[164:165], s[8:9], 0, v[4:5]
	v_and_b32_e32 v177, 7, v190
	v_mov_b32_e32 v178, v164
	v_mov_b32_e32 v179, v165
	v_cmp_eq_u32_e64 s[100:101], 1, v177
	s_nop 1
	v_cndmask_b32_e64 v178, v178, v162, s[100:101]
	v_cndmask_b32_e64 v179, v179, v163, s[100:101]
	v_cmp_eq_u32_e64 s[100:101], 2, v177
	s_nop 1
	v_cndmask_b32_e64 v178, v178, v160, s[100:101]
	v_cndmask_b32_e64 v179, v179, v161, s[100:101]
	v_cmp_eq_u32_e64 s[100:101], 3, v177
	s_nop 1
	v_cndmask_b32_e64 v178, v178, v158, s[100:101]
	v_cndmask_b32_e64 v179, v179, v159, s[100:101]
	v_cmp_eq_u32_e64 s[100:101], 4, v177
	s_nop 1
	v_cndmask_b32_e64 v178, v178, v156, s[100:101]
	v_cndmask_b32_e64 v179, v179, v157, s[100:101]
	v_cmp_eq_u32_e64 s[100:101], 5, v177
	s_nop 1
	v_cndmask_b32_e64 v178, v178, v154, s[100:101]
	v_cndmask_b32_e64 v179, v179, v155, s[100:101]
	v_cmp_eq_u32_e64 s[100:101], 6, v177
	s_nop 1
	v_cndmask_b32_e64 v178, v178, v152, s[100:101]
	v_cndmask_b32_e64 v179, v179, v153, s[100:101]
	v_cmp_eq_u32_e64 s[100:101], 7, v177
	s_nop 1
	v_cndmask_b32_e64 v178, v178, v146, s[100:101]
	v_cndmask_b32_e64 v179, v179, v147, s[100:101]
	s_nop 0
	global_load_dword v177, v[178:179], off offset:0 sc1
	s_mov_b64 s[2:3], 0
	s_mov_b32 s8, 0
	v_mov_b32_e32 v3, v2
	v_mov_b32_e32 v4, v2
	v_mov_b32_e32 v5, v2
	v_mov_b32_e32 v7, v6
	v_mov_b32_e32 v8, v6
	v_mov_b32_e32 v9, v6
	v_mov_b32_e32 v11, v10
	v_mov_b32_e32 v12, v10
	v_mov_b32_e32 v13, v10
	v_mov_b32_e32 v15, v14
	v_mov_b32_e32 v16, v14
	v_mov_b32_e32 v17, v14
	v_mov_b32_e32 v19, v18
	v_mov_b32_e32 v20, v18
	v_mov_b32_e32 v21, v18
	v_mov_b32_e32 v23, v22
	v_mov_b32_e32 v24, v22
	v_mov_b32_e32 v25, v22
	v_mov_b32_e32 v27, v26
	v_mov_b32_e32 v28, v26
	v_mov_b32_e32 v29, v26
	v_mov_b32_e32 v31, v30
	v_mov_b32_e32 v32, v30
	v_mov_b32_e32 v33, v30
	v_mov_b32_e32 v35, v34
	v_mov_b32_e32 v36, v34
	v_mov_b32_e32 v37, v34
	v_mov_b32_e32 v39, v38
	v_mov_b32_e32 v40, v38
	v_mov_b32_e32 v41, v38
	v_mov_b32_e32 v43, v42
	v_mov_b32_e32 v44, v42
	v_mov_b32_e32 v45, v42
	v_mov_b32_e32 v47, v46
	v_mov_b32_e32 v48, v46
	v_mov_b32_e32 v49, v46
	v_mov_b32_e32 v51, v50
	v_mov_b32_e32 v52, v50
	v_mov_b32_e32 v53, v50
	v_mov_b32_e32 v55, v54
	v_mov_b32_e32 v56, v54
	v_mov_b32_e32 v57, v54
	v_mov_b32_e32 v59, v58
	v_mov_b32_e32 v60, v58
	v_mov_b32_e32 v61, v58
	v_mov_b32_e32 v63, v62
	v_mov_b32_e32 v64, v62
	v_mov_b32_e32 v65, v62
	s_branch .LBB0_361

; #define MMSET(S)                                                                                                          \
;   _Pragma("unroll") for (int mi = 0; mi < 2; ++mi)                                                                        \
;   _Pragma("unroll") for (int ni = 0; ni < 8; ++ni) acc[mi][ni] = __builtin_amdgcn_mfma_f32_16x16x32_bf16(bfr[S][ni], af[S][mi], acc[mi][ni], 0, 0, 0);
; DI void gemm_mainloop_deep(const bf16_t* __restrict__ A, int lda, const bf16_t* __restrict__ Bt, int ldb, int K, int m0, int n0,
;                            f32x4 (&acc)[2][8], char* smem, bool prefetched) {
;     ...
;   for (int kt = 0; kt < nk; ++kt) {
;     const unsigned cb = lb + (kt & 1) * 32768, nb = lb + ((kt & 1) ^ 1) * 32768;
;     { const unsigned a = cb + wave * 4096 + o1, b = cb + 16384 + o1; RDSET(1, a, b); }
;     __builtin_amdgcn_sched_barrier(0);
;     asm volatile("s_waitcnt lgkmcnt(10)" ::: "memory");
;     __builtin_amdgcn_sched_barrier(0);
;     MMSET(0)
;     __builtin_amdgcn_sched_barrier(0);
;     asm volatile("s_waitcnt lgkmcnt(0)\n\ts_waitcnt vmcnt(0)" ::: "memory");
;     __syncthreads();
;     __builtin_amdgcn_sched_barrier(0);
;     if (kt + 2 < nk) { GSTAGE(kt & 1, kt + 2); }
.LBB0_361:
	s_and_b32 s9, s7, 0x8000
	v_or_b32_e32 v106, s9, v0
	v_add_u32_e32 v107, v106, v171
	ds_read_b128 v[110:113], v107 offset:0
	v_add_u32_e32 v142, v106, v172
	ds_read_b128 v[106:109], v107 offset:0x800
	ds_read_b128 v[114:117], v142 offset:0
	ds_read_b128 v[118:121], v142 offset:0x800
	ds_read_b128 v[122:125], v142 offset:0x1000
	ds_read_b128 v[126:129], v142 offset:0x1800
	ds_read_b128 v[130:133], v142 offset:0x2000
	ds_read_b128 v[134:137], v142 offset:0x2800
	ds_read_b128 v[138:141], v142 offset:0x3000
	ds_read_b128 v[142:145], v142 offset:0x3800
	s_waitcnt lgkmcnt(10)
	v_mfma_f32_16x16x32_bf16 v[62:65], v[74:77], v[66:69], v[62:65]
	v_mfma_f32_16x16x32_bf16 v[58:61], v[78:81], v[66:69], v[58:61]
	v_mfma_f32_16x16x32_bf16 v[54:57], v[82:85], v[66:69], v[54:57]
	v_mfma_f32_16x16x32_bf16 v[50:53], v[86:89], v[66:69], v[50:53]
	v_mfma_f32_16x16x32_bf16 v[46:49], v[90:93], v[66:69], v[46:49]
	v_mfma_f32_16x16x32_bf16 v[42:45], v[94:97], v[66:69], v[42:45]
	v_mfma_f32_16x16x32_bf16 v[38:41], v[98:101], v[66:69], v[38:41]
	v_mfma_f32_16x16x32_bf16 v[34:37], v[102:105], v[66:69], v[34:37]
	v_mfma_f32_16x16x32_bf16 v[30:33], v[74:77], v[70:73], v[30:33]
	v_mfma_f32_16x16x32_bf16 v[26:29], v[78:81], v[70:73], v[26:29]
	v_mfma_f32_16x16x32_bf16 v[22:25], v[82:85], v[70:73], v[22:25]
	v_mfma_f32_16x16x32_bf16 v[18:21], v[86:89], v[70:73], v[18:21]
	v_mfma_f32_16x16x32_bf16 v[14:17], v[90:93], v[70:73], v[14:17]
	v_mfma_f32_16x16x32_bf16 v[10:13], v[94:97], v[70:73], v[10:13]
	v_mfma_f32_16x16x32_bf16 v[6:9], v[98:101], v[70:73], v[6:9]
	v_mfma_f32_16x16x32_bf16 v[2:5], v[102:105], v[70:73], v[2:5]
	s_waitcnt lgkmcnt(0)
	s_waitcnt vmcnt(1)
	s_waitcnt vmcnt(1) lgkmcnt(0)
	s_barrier
	s_cmp_gt_u32 s8, 61
	s_cbranch_scc1 .LBB0_363
	v_add_u32_e32 v173, s9, v168
	v_add_u32_e32 v176, 0x4000, v173
	v_readfirstlane_b32 s10, v173
	v_lshl_add_u64 v[174:175], v[164:165], 0, s[2:3]
	s_mov_b32 m0, s10
	v_readfirstlane_b32 s10, v176
	v_add_u32_e32 v176, 0x1000, v173
	global_load_lds_dwordx4 v[174:175], off
	v_lshl_add_u64 v[174:175], v[162:163], 0, s[2:3]
	s_mov_b32 m0, s10
	v_readfirstlane_b32 s10, v176
	v_add_u32_e32 v176, 0x5000, v173
	global_load_lds_dwordx4 v[174:175], off
	v_lshl_add_u64 v[174:175], v[160:161], 0, s[2:3]
	s_mov_b32 m0, s10
	v_readfirstlane_b32 s10, v176
	v_add_u32_e32 v176, 0x2000, v173
	global_load_lds_dwordx4 v[174:175], off
	v_lshl_add_u64 v[174:175], v[158:159], 0, s[2:3]
	s_mov_b32 m0, s10
	v_readfirstlane_b32 s10, v176
	v_add_u32_e32 v176, 0x6000, v173
	global_load_lds_dwordx4 v[174:175], off
	v_lshl_add_u64 v[174:175], v[156:157], 0, s[2:3]
	s_mov_b32 m0, s10
	v_readfirstlane_b32 s10, v176
	v_add_u32_e32 v176, 0x3000, v173
	global_load_lds_dwordx4 v[174:175], off
	v_lshl_add_u64 v[174:175], v[154:155], 0, s[2:3]
	s_mov_b32 m0, s10
	v_readfirstlane_b32 s10, v176
	v_add_u32_e32 v173, 0x7000, v173
	global_load_lds_dwordx4 v[174:175], off
	v_lshl_add_u64 v[174:175], v[152:153], 0, s[2:3]
	s_mov_b32 m0, s10
	v_readfirstlane_b32 s10, v173
	global_load_lds_dwordx4 v[174:175], off
	v_lshl_add_u64 v[174:175], v[146:147], 0, s[2:3]
	s_mov_b32 m0, s10
	s_nop 0
	global_load_lds_dwordx4 v[174:175], off
	v_lshl_add_u64 v[180:181], v[178:179], 0, s[2:3]
	global_load_dword v177, v[180:181], off offset:128 sc1

; template <int QS>
; DI void nsa_cmpwin_item(int item, const bf16_t* __restrict__ z, const bf16_t* __restrict__ kcmp, const bf16_t* __restrict__ vcmp,
;                                 const float* __restrict__ bgate, float* __restrict__ P, float* __restrict__ part, char* smem) {
;     ...
; #pragma unroll
;     for (int qs = 0; qs < QS; ++qs) {
;       float lt = l[qs]; lt += __shfl_xor(lt, 16); lt += __shfl_xor(lt, 32);
;       const float inv = (lt > 0.f ? 1.f / lt : 0.f) * nsa_gate(z, bgate, tb + qi[qs], hh, 2);
;       float* op = part + (tb + qi[qs]) * DM + hh * 128;
; #pragma unroll
;       for (int dt = 0; dt < 8; ++dt) { f32x4 pv = *(f32x4*)(op + dt * 16 + 4 * g); pv += o[qs][dt] * inv; *(f32x4*)(op + dt * 16 + 4 * g) = pv; }
;     }
.LBB0_484:
	s_mov_b64 s[80:81], s[14:15]
	v_mad_u64_u32 v[4:5], s[0:1], v138, s94, 0
	s_add_u32 s4, s86, s80
	v_mad_i32_i24 v5, v139, s94, v5
	s_addc_u32 s5, s87, 0
	v_lshl_add_u64 v[4:5], s[4:5], 0, v[4:5]
	v_add_co_u32_e32 v4, vcc, 0x2000, v4
	global_load_dword v10, v1, s[2:3] offset:8
	s_nop 0
	v_addc_co_u32_e32 v5, vcc, 0, v5, vcc
	global_load_ushort v0, v[4:5], off offset:2052
	ds_bpermute_b32 v7, v180, v155
	v_mad_u64_u32 v[2:3], s[0:1], v140, s94, 0
	v_mad_i32_i24 v3, v141, s94, v3
	v_lshl_add_u64 v[2:3], s[4:5], 0, v[2:3]
	v_readlane_b32 s4, v254, 50
	s_movk_i32 s69, 0xe0
	s_waitcnt vmcnt(0)
	v_lshlrev_b32_e32 v0, 16, v0
	v_add_f32_e32 v0, v10, v0
	v_mul_f32_e32 v0, 0xbfb8aa3b, v0
	v_exp_f32_e32 v0, v0
	s_nop 0
	v_add_f32_e32 v0, 1.0, v0
	v_div_scale_f32 v4, s[0:1], v0, v0, 1.0
	v_rcp_f32_e32 v5, v4
	s_nop 0
	v_fma_f32 v6, -v4, v5, 1.0
	v_fmac_f32_e32 v5, v6, v5
	v_div_scale_f32 v6, vcc, 1.0, v0, 1.0
	v_mul_f32_e32 v8, v6, v5
	v_fma_f32 v9, -v4, v8, v6
	v_fmac_f32_e32 v8, v9, v5
	v_fma_f32 v4, -v4, v8, v6
	ds_bpermute_b32 v6, v180, v154
	v_div_fmas_f32 v4, v4, v5, v8
	v_div_fixup_f32 v0, v4, v0, 1.0
	s_waitcnt lgkmcnt(0)
	v_pk_add_f32 v[4:5], v[154:155], v[6:7]
	ds_bpermute_b32 v7, v181, v5
	ds_bpermute_b32 v6, v181, v4
	s_waitcnt lgkmcnt(0)
	v_pk_add_f32 v[8:9], v[4:5], v[6:7]
	s_nop 0
	v_div_scale_f32 v4, s[0:1], v9, v9, 1.0
	v_rcp_f32_e32 v5, v4
	v_cmp_lt_f32_e64 s[0:1], 0, v8
	v_fma_f32 v6, -v4, v5, 1.0
	v_fmac_f32_e32 v5, v6, v5
	v_div_scale_f32 v6, vcc, 1.0, v9, 1.0
	v_mul_f32_e32 v7, v6, v5
	v_fma_f32 v11, -v4, v7, v6
	v_fmac_f32_e32 v7, v11, v5
	v_fma_f32 v4, -v4, v7, v6
	v_div_fmas_f32 v4, v4, v5, v7
	v_div_fixup_f32 v4, v4, v9, 1.0
	v_cmp_lt_f32_e32 vcc, 0, v9
	s_nop 1
	v_cndmask_b32_e32 v4, 0, v4, vcc
	v_mul_f32_e32 v0, v4, v0
	v_pk_fma_f32 v[6:7], v[68:69], v[0:1], v[100:101] op_sel_hi:[1,0,1]
	v_pk_fma_f32 v[4:5], v[66:67], v[0:1], v[98:99] op_sel_hi:[1,0,1]
	global_store_dwordx4 v[132:133], v[4:7], off
	s_nop 1
	v_pk_fma_f32 v[6:7], v[72:73], v[0:1], v[104:105] op_sel_hi:[1,0,1]
	v_pk_fma_f32 v[4:5], v[70:71], v[0:1], v[102:103] op_sel_hi:[1,0,1]
	global_store_dwordx4 v[132:133], v[4:7], off offset:64
	s_nop 1
	v_pk_fma_f32 v[6:7], v[76:77], v[0:1], v[108:109] op_sel_hi:[1,0,1]
	v_pk_fma_f32 v[4:5], v[74:75], v[0:1], v[106:107] op_sel_hi:[1,0,1]
	global_store_dwordx4 v[132:133], v[4:7], off offset:128
	s_nop 1
	v_pk_fma_f32 v[6:7], v[80:81], v[0:1], v[112:113] op_sel_hi:[1,0,1]
	v_pk_fma_f32 v[4:5], v[78:79], v[0:1], v[110:111] op_sel_hi:[1,0,1]
	global_store_dwordx4 v[132:133], v[4:7], off offset:192
	s_nop 1
	v_pk_fma_f32 v[6:7], v[84:85], v[0:1], v[116:117] op_sel_hi:[1,0,1]
	v_pk_fma_f32 v[4:5], v[82:83], v[0:1], v[114:115] op_sel_hi:[1,0,1]
	global_store_dwordx4 v[132:133], v[4:7], off offset:256
	s_nop 1
	v_pk_fma_f32 v[6:7], v[88:89], v[0:1], v[120:121] op_sel_hi:[1,0,1]
	v_pk_fma_f32 v[4:5], v[86:87], v[0:1], v[118:119] op_sel_hi:[1,0,1]
	global_store_dwordx4 v[132:133], v[4:7], off offset:320
	s_nop 1
	v_pk_fma_f32 v[6:7], v[92:93], v[0:1], v[124:125] op_sel_hi:[1,0,1]
	v_pk_fma_f32 v[4:5], v[90:91], v[0:1], v[122:123] op_sel_hi:[1,0,1]
	global_store_dwordx4 v[132:133], v[4:7], off offset:384
	s_nop 1
	v_pk_fma_f32 v[6:7], v[96:97], v[0:1], v[128:129] op_sel_hi:[1,0,1]
	v_pk_fma_f32 v[4:5], v[94:95], v[0:1], v[126:127] op_sel_hi:[1,0,1]
	v_div_scale_f32 v0, s[2:3], v8, v8, 1.0
	global_store_dwordx4 v[132:133], v[4:7], off offset:448
	s_nop 1
	v_rcp_f32_e32 v4, v0
	s_nop 0
	v_fma_f32 v5, -v0, v4, 1.0
	v_fmac_f32_e32 v4, v5, v4
	v_div_scale_f32 v5, vcc, 1.0, v8, 1.0
	v_mul_f32_e32 v6, v5, v4
	v_fma_f32 v7, -v0, v6, v5
	v_fmac_f32_e32 v6, v7, v4
	v_fma_f32 v0, -v0, v6, v5
	v_div_fmas_f32 v0, v0, v4, v6
	v_add_co_u32_e32 v2, vcc, s93, v2
	v_div_fixup_f32 v0, v0, v8, 1.0
	s_nop 0
	v_addc_co_u32_e32 v3, vcc, 0, v3, vcc
	global_load_ushort v2, v[2:3], off offset:2052
	v_cndmask_b32_e64 v0, 0, v0, s[0:1]
	s_waitcnt vmcnt(0)
	v_lshlrev_b32_e32 v2, 16, v2
	v_add_f32_e32 v2, v10, v2
	v_mul_f32_e32 v2, 0xbfb8aa3b, v2
	v_exp_f32_e32 v2, v2
	s_nop 0
	v_add_f32_e32 v2, 1.0, v2
	v_div_scale_f32 v3, s[0:1], v2, v2, 1.0
	v_rcp_f32_e32 v4, v3
	v_readlane_b32 s0, v253, 52
	s_add_i32 s4, s4, s0
	s_cmpk_gt_i32 s4, 0x3ff
	v_fma_f32 v5, -v3, v4, 1.0
	v_fmac_f32_e32 v4, v5, v4
	v_div_scale_f32 v5, vcc, 1.0, v2, 1.0
	v_mul_f32_e32 v6, v5, v4
	v_fma_f32 v7, -v3, v6, v5
	v_fmac_f32_e32 v6, v7, v4
	v_fma_f32 v3, -v3, v6, v5
	v_div_fmas_f32 v3, v3, v4, v6
	v_div_fixup_f32 v2, v3, v2, 1.0
	v_mul_f32_e32 v0, v0, v2
	global_load_dwordx4 v[108:111], v[130:131], off
	global_load_dwordx4 v[112:115], v[130:131], off offset:64
	global_load_dwordx4 v[116:119], v[130:131], off offset:128
	global_load_dwordx4 v[120:123], v[130:131], off offset:192
	global_load_dwordx4 v[124:127], v[130:131], off offset:256
	global_load_dwordx4 v[132:135], v[130:131], off offset:320
	global_load_dwordx4 v[136:139], v[130:131], off offset:384
	global_load_dwordx4 v[140:143], v[130:131], off offset:448
	v_readlane_b32 s1, v253, 53
	s_waitcnt vmcnt(7)
	v_pk_fma_f32 v[110:111], v[48:49], v[0:1], v[110:111] op_sel_hi:[1,0,1]
	v_pk_fma_f32 v[108:109], v[46:47], v[0:1], v[108:109] op_sel_hi:[1,0,1]
	global_store_dwordx4 v[130:131], v[108:111], off
	s_waitcnt vmcnt(7)
	v_pk_fma_f32 v[114:115], v[40:41], v[0:1], v[114:115] op_sel_hi:[1,0,1]
	v_pk_fma_f32 v[112:113], v[38:39], v[0:1], v[112:113] op_sel_hi:[1,0,1]
	global_store_dwordx4 v[130:131], v[112:115], off offset:64
	s_waitcnt vmcnt(7)
	v_pk_fma_f32 v[118:119], v[44:45], v[0:1], v[118:119] op_sel_hi:[1,0,1]
	v_pk_fma_f32 v[116:117], v[42:43], v[0:1], v[116:117] op_sel_hi:[1,0,1]
	global_store_dwordx4 v[130:131], v[116:119], off offset:128
	s_waitcnt vmcnt(7)
	v_pk_fma_f32 v[120:121], v[50:51], v[0:1], v[120:121] op_sel_hi:[1,0,1]
	v_pk_fma_f32 v[122:123], v[52:53], v[0:1], v[122:123] op_sel_hi:[1,0,1]
	global_store_dwordx4 v[130:131], v[120:123], off offset:192
	s_waitcnt vmcnt(7)
	v_pk_fma_f32 v[124:125], v[54:55], v[0:1], v[124:125] op_sel_hi:[1,0,1]
	v_pk_fma_f32 v[126:127], v[56:57], v[0:1], v[126:127] op_sel_hi:[1,0,1]
	global_store_dwordx4 v[130:131], v[124:127], off offset:256
	s_waitcnt vmcnt(7)
	v_pk_fma_f32 v[132:133], v[58:59], v[0:1], v[132:133] op_sel_hi:[1,0,1]
	v_pk_fma_f32 v[134:135], v[60:61], v[0:1], v[134:135] op_sel_hi:[1,0,1]
	global_store_dwordx4 v[130:131], v[132:135], off offset:320
	s_waitcnt vmcnt(7)
	v_pk_fma_f32 v[136:137], v[62:63], v[0:1], v[136:137] op_sel_hi:[1,0,1]
	v_pk_fma_f32 v[138:139], v[64:65], v[0:1], v[138:139] op_sel_hi:[1,0,1]
	global_store_dwordx4 v[130:131], v[136:139], off offset:384
	s_waitcnt vmcnt(7)
	v_pk_fma_f32 v[140:141], v[34:35], v[0:1], v[140:141] op_sel_hi:[1,0,1]
	v_pk_fma_f32 v[142:143], v[36:37], v[0:1], v[142:143] op_sel_hi:[1,0,1]
	global_store_dwordx4 v[130:131], v[140:143], off offset:448
	s_cbranch_scc1 .LBB0_502

; DI unsigned pack2(float lo, float hi) { unsigned r; asm("v_cvt_pk_bf16_f32 %0, %1, %2" : "=v"(r) : "v"(lo), "v"(hi)); return r; }
; template <int QS>
; DI void nsa_sel_item(int item, const bf16_t* __restrict__ z, const unsigned* __restrict__ sel, const float* __restrict__ bgate,
;                              const float* __restrict__ part, bf16_t* __restrict__ mix, char* smem) {
;     ...
; #pragma unroll
;   for (int qs = 0; qs < QS; ++qs) {
;     float lt = l[qs]; lt += __shfl_xor(lt, 16); lt += __shfl_xor(lt, 32);
;     const float inv = (lt > 0.f ? 1.f / lt : 0.f) * nsa_gate(z, bgate, tb + qi[qs], hh, 1);
;     const float* pp = part + (tb + qi[qs]) * DM + hh * 128;
;     bf16_t* op = mix + (tb + qi[qs]) * DM + hh * 128;
; #pragma unroll
;     for (int dt = 0; dt < 8; ++dt) {
;       const f32x4 pv = *(const f32x4*)(pp + dt * 16 + 4 * g);
;       uint2 w; w.x = pack2(pv[0] + o[qs][dt][0] * inv, pv[1] + o[qs][dt][1] * inv); w.y = pack2(pv[2] + o[qs][dt][2] * inv, pv[3] + o[qs][dt][3] * inv);
;       *(uint2*)(op + dt * 16 + 4 * g) = w;
.LBB0_609:
	s_lshl_b32 s4, s28, 7
	v_mad_u64_u32 v[70:71], s[0:1], v132, s94, 0
	v_mad_u64_u32 v[66:67], s[0:1], v130, s94, 0
	s_mul_i32 s28, s28, 3
	v_cmp_lt_i32_e32 vcc, v137, v135
	s_lshl_b32 s0, s28, 1
	s_add_u32 s2, s86, s0
	v_cndmask_b32_e32 v0, v198, v137, vcc
	v_cmp_lt_i32_e32 vcc, v169, v135
	v_lshlrev_b32_e32 v69, 2, v0
	s_addc_u32 s3, s87, 0
	v_cndmask_b32_e32 v0, v198, v169, vcc
	s_lshl_b32 s0, s28, 2
	v_lshlrev_b32_e32 v78, 2, v0
	v_mov_b32_e32 v0, s0
	v_readlane_b32 s0, v254, 48
	v_readlane_b32 s1, v254, 49
	v_readlane_b32 s6, v251, 32
	v_readlane_b32 s7, v251, 33
	v_mad_i32_i24 v71, v133, s94, v71
	v_lshl_add_u64 v[70:71], s[2:3], 0, v[70:71]
	v_mad_i32_i24 v67, v131, s94, v67
	global_load_dword v68, v0, s[0:1] offset:4
	s_lshl_b32 s0, s4, 2
	s_add_u32 s0, s84, s0
	v_lshrrev_b32_e32 v0, 2, v168
	s_addc_u32 s1, s85, 0
	s_lshl_b32 s4, s4, 1
	v_and_b32_e32 v64, 12, v0
	s_add_u32 s4, s6, s4
	v_lshlrev_b32_e32 v0, 2, v64
	s_addc_u32 s5, s7, 0
	v_lshl_add_u64 v[62:63], s[0:1], 0, v[0:1]
	v_lshlrev_b32_e32 v0, 1, v64
	v_lshl_add_u64 v[64:65], s[4:5], 0, v[0:1]
	ds_bpermute_b32 v0, v69, v107
	s_waitcnt lgkmcnt(0)
	v_add_f32_e32 v0, v107, v0
	ds_bpermute_b32 v72, v78, v0
	s_waitcnt lgkmcnt(0)
	v_add_f32_e32 v0, v0, v72
	v_div_scale_f32 v72, s[4:5], v0, v0, 1.0
	v_rcp_f32_e32 v73, v72
	v_cmp_lt_f32_e64 s[0:1], 0, v0
	v_fma_f32 v74, -v72, v73, 1.0
	v_fmac_f32_e32 v73, v74, v73
	v_div_scale_f32 v74, vcc, 1.0, v0, 1.0
	v_mul_f32_e32 v75, v74, v73
	v_fma_f32 v76, -v72, v75, v74
	v_fmac_f32_e32 v75, v76, v73
	v_fma_f32 v72, -v72, v75, v74
	v_div_fmas_f32 v72, v72, v73, v75
	v_add_co_u32_e32 v70, vcc, s93, v70
	v_div_fixup_f32 v0, v72, v0, 1.0
	s_nop 0
	v_addc_co_u32_e32 v71, vcc, 0, v71, vcc
	global_load_ushort v70, v[70:71], off offset:2050
	v_cndmask_b32_e64 v0, 0, v0, s[0:1]
	s_waitcnt vmcnt(0)
	v_lshlrev_b32_e32 v70, 16, v70
	v_add_f32_e32 v70, v68, v70
	v_mul_f32_e32 v70, 0xbfb8aa3b, v70
	v_exp_f32_e32 v70, v70
	s_nop 0
	v_add_f32_e32 v70, 1.0, v70
	v_div_scale_f32 v71, s[0:1], v70, v70, 1.0
	v_rcp_f32_e32 v72, v71
	s_nop 0
	v_fma_f32 v73, -v71, v72, 1.0
	v_fmac_f32_e32 v72, v73, v72
	v_div_scale_f32 v73, vcc, 1.0, v70, 1.0
	v_mul_f32_e32 v74, v73, v72
	v_fma_f32 v75, -v71, v74, v73
	v_fmac_f32_e32 v74, v75, v72
	v_fma_f32 v71, -v71, v74, v73
	v_div_fmas_f32 v71, v71, v72, v74
	v_div_fixup_f32 v70, v71, v70, 1.0
	v_mul_f32_e32 v0, v0, v70
	v_lshlrev_b64 v[70:71], 13, v[132:133]
	v_lshl_add_u64 v[74:75], v[62:63], 0, v[70:71]
	v_lshlrev_b64 v[70:71], 12, v[132:133]
	v_lshl_add_u64 v[76:77], v[64:65], 0, v[70:71]
	global_load_dwordx4 v[108:111], v[74:75], off
	global_load_dwordx4 v[112:115], v[74:75], off offset:64
	global_load_dwordx4 v[116:119], v[74:75], off offset:128
	global_load_dwordx4 v[120:123], v[74:75], off offset:192
	global_load_dwordx4 v[124:127], v[74:75], off offset:256
	global_load_dwordx4 v[132:135], v[74:75], off offset:320
	global_load_dwordx4 v[136:139], v[74:75], off offset:384
	global_load_dwordx4 v[140:143], v[74:75], off offset:448
	s_waitcnt vmcnt(7)
	v_fma_f32 v54, v54, v0, v108
	v_fma_f32 v55, v55, v0, v109

; DI unsigned pack2(float lo, float hi) { unsigned r; asm("v_cvt_pk_bf16_f32 %0, %1, %2" : "=v"(r) : "v"(lo), "v"(hi)); return r; }
; template <int QS>
; DI void nsa_sel_item(int item, const bf16_t* __restrict__ z, const unsigned* __restrict__ sel, const float* __restrict__ bgate,
;                              const float* __restrict__ part, bf16_t* __restrict__ mix, char* smem) {
;     ...
;     for (int dt = 0; dt < 8; ++dt) {
;       const f32x4 pv = *(const f32x4*)(pp + dt * 16 + 4 * g);
;       uint2 w; w.x = pack2(pv[0] + o[qs][dt][0] * inv, pv[1] + o[qs][dt][1] * inv); w.y = pack2(pv[2] + o[qs][dt][2] * inv, pv[3] + o[qs][dt][3] * inv);
;       *(uint2*)(op + dt * 16 + 4 * g) = w;
	v_cvt_pk_bf16_f32 v54, v54, v55

; DI unsigned pack2(float lo, float hi) { unsigned r; asm("v_cvt_pk_bf16_f32 %0, %1, %2" : "=v"(r) : "v"(lo), "v"(hi)); return r; }
; template <int QS>
; DI void nsa_sel_item(int item, const bf16_t* __restrict__ z, const unsigned* __restrict__ sel, const float* __restrict__ bgate,
;                              const float* __restrict__ part, bf16_t* __restrict__ mix, char* smem) {
;     ...
;     for (int dt = 0; dt < 8; ++dt) {
;       const f32x4 pv = *(const f32x4*)(pp + dt * 16 + 4 * g);
;       uint2 w; w.x = pack2(pv[0] + o[qs][dt][0] * inv, pv[1] + o[qs][dt][1] * inv); w.y = pack2(pv[2] + o[qs][dt][2] * inv, pv[3] + o[qs][dt][3] * inv);
;       *(uint2*)(op + dt * 16 + 4 * g) = w;
	v_fma_f32 v55, v56, v0, v110
	v_fmac_f32_e32 v111, v57, v0

; DI unsigned pack2(float lo, float hi) { unsigned r; asm("v_cvt_pk_bf16_f32 %0, %1, %2" : "=v"(r) : "v"(lo), "v"(hi)); return r; }
; template <int QS>
; DI void nsa_sel_item(int item, const bf16_t* __restrict__ z, const unsigned* __restrict__ sel, const float* __restrict__ bgate,
;                              const float* __restrict__ part, bf16_t* __restrict__ mix, char* smem) {
;     ...
;     for (int dt = 0; dt < 8; ++dt) {
;       const f32x4 pv = *(const f32x4*)(pp + dt * 16 + 4 * g);
;       uint2 w; w.x = pack2(pv[0] + o[qs][dt][0] * inv, pv[1] + o[qs][dt][1] * inv); w.y = pack2(pv[2] + o[qs][dt][2] * inv, pv[3] + o[qs][dt][3] * inv);
;       *(uint2*)(op + dt * 16 + 4 * g) = w;
	v_cvt_pk_bf16_f32 v55, v55, v111

; DI unsigned pack2(float lo, float hi) { unsigned r; asm("v_cvt_pk_bf16_f32 %0, %1, %2" : "=v"(r) : "v"(lo), "v"(hi)); return r; }
; template <int QS>
; DI void nsa_sel_item(int item, const bf16_t* __restrict__ z, const unsigned* __restrict__ sel, const float* __restrict__ bgate,
;                              const float* __restrict__ part, bf16_t* __restrict__ mix, char* smem) {
;     ...
;     for (int dt = 0; dt < 8; ++dt) {
;       const f32x4 pv = *(const f32x4*)(pp + dt * 16 + 4 * g);
;       uint2 w; w.x = pack2(pv[0] + o[qs][dt][0] * inv, pv[1] + o[qs][dt][1] * inv); w.y = pack2(pv[2] + o[qs][dt][2] * inv, pv[3] + o[qs][dt][3] * inv);
;       *(uint2*)(op + dt * 16 + 4 * g) = w;
	global_store_dwordx2 v[76:77], v[54:55], off
	s_waitcnt vmcnt(7)
	v_fma_f32 v42, v42, v0, v112
	v_fma_f32 v43, v43, v0, v113

; DI unsigned pack2(float lo, float hi) { unsigned r; asm("v_cvt_pk_bf16_f32 %0, %1, %2" : "=v"(r) : "v"(lo), "v"(hi)); return r; }
; template <int QS>
; DI void nsa_sel_item(int item, const bf16_t* __restrict__ z, const unsigned* __restrict__ sel, const float* __restrict__ bgate,
;                              const float* __restrict__ part, bf16_t* __restrict__ mix, char* smem) {
;     ...
;     for (int dt = 0; dt < 8; ++dt) {
;       const f32x4 pv = *(const f32x4*)(pp + dt * 16 + 4 * g);
;       uint2 w; w.x = pack2(pv[0] + o[qs][dt][0] * inv, pv[1] + o[qs][dt][1] * inv); w.y = pack2(pv[2] + o[qs][dt][2] * inv, pv[3] + o[qs][dt][3] * inv);
;       *(uint2*)(op + dt * 16 + 4 * g) = w;
	v_cvt_pk_bf16_f32 v42, v42, v43

; DI unsigned pack2(float lo, float hi) { unsigned r; asm("v_cvt_pk_bf16_f32 %0, %1, %2" : "=v"(r) : "v"(lo), "v"(hi)); return r; }
; template <int QS>
; DI void nsa_sel_item(int item, const bf16_t* __restrict__ z, const unsigned* __restrict__ sel, const float* __restrict__ bgate,
;                              const float* __restrict__ part, bf16_t* __restrict__ mix, char* smem) {
;     ...
;     for (int dt = 0; dt < 8; ++dt) {
;       const f32x4 pv = *(const f32x4*)(pp + dt * 16 + 4 * g);
;       uint2 w; w.x = pack2(pv[0] + o[qs][dt][0] * inv, pv[1] + o[qs][dt][1] * inv); w.y = pack2(pv[2] + o[qs][dt][2] * inv, pv[3] + o[qs][dt][3] * inv);
;       *(uint2*)(op + dt * 16 + 4 * g) = w;
	v_fma_f32 v43, v44, v0, v114
	v_fmac_f32_e32 v115, v45, v0

; DI unsigned pack2(float lo, float hi) { unsigned r; asm("v_cvt_pk_bf16_f32 %0, %1, %2" : "=v"(r) : "v"(lo), "v"(hi)); return r; }
; template <int QS>
; DI void nsa_sel_item(int item, const bf16_t* __restrict__ z, const unsigned* __restrict__ sel, const float* __restrict__ bgate,
;                              const float* __restrict__ part, bf16_t* __restrict__ mix, char* smem) {
;     ...
;     for (int dt = 0; dt < 8; ++dt) {
;       const f32x4 pv = *(const f32x4*)(pp + dt * 16 + 4 * g);
;       uint2 w; w.x = pack2(pv[0] + o[qs][dt][0] * inv, pv[1] + o[qs][dt][1] * inv); w.y = pack2(pv[2] + o[qs][dt][2] * inv, pv[3] + o[qs][dt][3] * inv);
;       *(uint2*)(op + dt * 16 + 4 * g) = w;
	v_cvt_pk_bf16_f32 v43, v43, v115

; DI unsigned pack2(float lo, float hi) { unsigned r; asm("v_cvt_pk_bf16_f32 %0, %1, %2" : "=v"(r) : "v"(lo), "v"(hi)); return r; }
; template <int QS>
; DI void nsa_sel_item(int item, const bf16_t* __restrict__ z, const unsigned* __restrict__ sel, const float* __restrict__ bgate,
;                              const float* __restrict__ part, bf16_t* __restrict__ mix, char* smem) {
;     ...
;     for (int dt = 0; dt < 8; ++dt) {
;       const f32x4 pv = *(const f32x4*)(pp + dt * 16 + 4 * g);
;       uint2 w; w.x = pack2(pv[0] + o[qs][dt][0] * inv, pv[1] + o[qs][dt][1] * inv); w.y = pack2(pv[2] + o[qs][dt][2] * inv, pv[3] + o[qs][dt][3] * inv);
;       *(uint2*)(op + dt * 16 + 4 * g) = w;
	global_store_dwordx2 v[76:77], v[42:43], off offset:32
	s_waitcnt vmcnt(7)
	v_fma_f32 v116, v46, v0, v116
	v_fma_f32 v117, v47, v0, v117

; DI unsigned pack2(float lo, float hi) { unsigned r; asm("v_cvt_pk_bf16_f32 %0, %1, %2" : "=v"(r) : "v"(lo), "v"(hi)); return r; }
; template <int QS>
; DI void nsa_sel_item(int item, const bf16_t* __restrict__ z, const unsigned* __restrict__ sel, const float* __restrict__ bgate,
;                              const float* __restrict__ part, bf16_t* __restrict__ mix, char* smem) {
;     ...
;     for (int dt = 0; dt < 8; ++dt) {
;       const f32x4 pv = *(const f32x4*)(pp + dt * 16 + 4 * g);
;       uint2 w; w.x = pack2(pv[0] + o[qs][dt][0] * inv, pv[1] + o[qs][dt][1] * inv); w.y = pack2(pv[2] + o[qs][dt][2] * inv, pv[3] + o[qs][dt][3] * inv);
;       *(uint2*)(op + dt * 16 + 4 * g) = w;
	v_cvt_pk_bf16_f32 v116, v116, v117

; DI unsigned pack2(float lo, float hi) { unsigned r; asm("v_cvt_pk_bf16_f32 %0, %1, %2" : "=v"(r) : "v"(lo), "v"(hi)); return r; }
; template <int QS>
; DI void nsa_sel_item(int item, const bf16_t* __restrict__ z, const unsigned* __restrict__ sel, const float* __restrict__ bgate,
;                              const float* __restrict__ part, bf16_t* __restrict__ mix, char* smem) {
;     ...
;     for (int dt = 0; dt < 8; ++dt) {
;       const f32x4 pv = *(const f32x4*)(pp + dt * 16 + 4 * g);
;       uint2 w; w.x = pack2(pv[0] + o[qs][dt][0] * inv, pv[1] + o[qs][dt][1] * inv); w.y = pack2(pv[2] + o[qs][dt][2] * inv, pv[3] + o[qs][dt][3] * inv);
;       *(uint2*)(op + dt * 16 + 4 * g) = w;
	v_fma_f32 v117, v48, v0, v118
	v_fmac_f32_e32 v119, v49, v0

; DI unsigned pack2(float lo, float hi) { unsigned r; asm("v_cvt_pk_bf16_f32 %0, %1, %2" : "=v"(r) : "v"(lo), "v"(hi)); return r; }
; template <int QS>
; DI void nsa_sel_item(int item, const bf16_t* __restrict__ z, const unsigned* __restrict__ sel, const float* __restrict__ bgate,
;                              const float* __restrict__ part, bf16_t* __restrict__ mix, char* smem) {
;     ...
;     for (int dt = 0; dt < 8; ++dt) {
;       const f32x4 pv = *(const f32x4*)(pp + dt * 16 + 4 * g);
;       uint2 w; w.x = pack2(pv[0] + o[qs][dt][0] * inv, pv[1] + o[qs][dt][1] * inv); w.y = pack2(pv[2] + o[qs][dt][2] * inv, pv[3] + o[qs][dt][3] * inv);
;       *(uint2*)(op + dt * 16 + 4 * g) = w;
	v_cvt_pk_bf16_f32 v117, v117, v119

; DI unsigned pack2(float lo, float hi) { unsigned r; asm("v_cvt_pk_bf16_f32 %0, %1, %2" : "=v"(r) : "v"(lo), "v"(hi)); return r; }
; template <int QS>
; DI void nsa_sel_item(int item, const bf16_t* __restrict__ z, const unsigned* __restrict__ sel, const float* __restrict__ bgate,
;                              const float* __restrict__ part, bf16_t* __restrict__ mix, char* smem) {
;     ...
;     for (int dt = 0; dt < 8; ++dt) {
;       const f32x4 pv = *(const f32x4*)(pp + dt * 16 + 4 * g);
;       uint2 w; w.x = pack2(pv[0] + o[qs][dt][0] * inv, pv[1] + o[qs][dt][1] * inv); w.y = pack2(pv[2] + o[qs][dt][2] * inv, pv[3] + o[qs][dt][3] * inv);
;       *(uint2*)(op + dt * 16 + 4 * g) = w;
	global_store_dwordx2 v[76:77], v[116:117], off offset:64
	s_waitcnt vmcnt(7)
	v_fma_f32 v34, v34, v0, v120
	v_fma_f32 v35, v35, v0, v121

; DI unsigned pack2(float lo, float hi) { unsigned r; asm("v_cvt_pk_bf16_f32 %0, %1, %2" : "=v"(r) : "v"(lo), "v"(hi)); return r; }
; template <int QS>
; DI void nsa_sel_item(int item, const bf16_t* __restrict__ z, const unsigned* __restrict__ sel, const float* __restrict__ bgate,
;                              const float* __restrict__ part, bf16_t* __restrict__ mix, char* smem) {
;     ...
;     for (int dt = 0; dt < 8; ++dt) {
;       const f32x4 pv = *(const f32x4*)(pp + dt * 16 + 4 * g);
;       uint2 w; w.x = pack2(pv[0] + o[qs][dt][0] * inv, pv[1] + o[qs][dt][1] * inv); w.y = pack2(pv[2] + o[qs][dt][2] * inv, pv[3] + o[qs][dt][3] * inv);
;       *(uint2*)(op + dt * 16 + 4 * g) = w;
	v_cvt_pk_bf16_f32 v34, v34, v35

; DI unsigned pack2(float lo, float hi) { unsigned r; asm("v_cvt_pk_bf16_f32 %0, %1, %2" : "=v"(r) : "v"(lo), "v"(hi)); return r; }
; template <int QS>
; DI void nsa_sel_item(int item, const bf16_t* __restrict__ z, const unsigned* __restrict__ sel, const float* __restrict__ bgate,
;                              const float* __restrict__ part, bf16_t* __restrict__ mix, char* smem) {
;     ...
;     for (int dt = 0; dt < 8; ++dt) {
;       const f32x4 pv = *(const f32x4*)(pp + dt * 16 + 4 * g);
;       uint2 w; w.x = pack2(pv[0] + o[qs][dt][0] * inv, pv[1] + o[qs][dt][1] * inv); w.y = pack2(pv[2] + o[qs][dt][2] * inv, pv[3] + o[qs][dt][3] * inv);
;       *(uint2*)(op + dt * 16 + 4 * g) = w;
	v_fma_f32 v35, v36, v0, v122
	v_fmac_f32_e32 v123, v37, v0

; DI unsigned pack2(float lo, float hi) { unsigned r; asm("v_cvt_pk_bf16_f32 %0, %1, %2" : "=v"(r) : "v"(lo), "v"(hi)); return r; }
; template <int QS>
; DI void nsa_sel_item(int item, const bf16_t* __restrict__ z, const unsigned* __restrict__ sel, const float* __restrict__ bgate,
;                              const float* __restrict__ part, bf16_t* __restrict__ mix, char* smem) {
;     ...
;     for (int dt = 0; dt < 8; ++dt) {
;       const f32x4 pv = *(const f32x4*)(pp + dt * 16 + 4 * g);
;       uint2 w; w.x = pack2(pv[0] + o[qs][dt][0] * inv, pv[1] + o[qs][dt][1] * inv); w.y = pack2(pv[2] + o[qs][dt][2] * inv, pv[3] + o[qs][dt][3] * inv);
;       *(uint2*)(op + dt * 16 + 4 * g) = w;
	v_cvt_pk_bf16_f32 v35, v35, v123

; DI unsigned pack2(float lo, float hi) { unsigned r; asm("v_cvt_pk_bf16_f32 %0, %1, %2" : "=v"(r) : "v"(lo), "v"(hi)); return r; }
; template <int QS>
; DI void nsa_sel_item(int item, const bf16_t* __restrict__ z, const unsigned* __restrict__ sel, const float* __restrict__ bgate,
;                              const float* __restrict__ part, bf16_t* __restrict__ mix, char* smem) {
;     ...
;     for (int dt = 0; dt < 8; ++dt) {
;       const f32x4 pv = *(const f32x4*)(pp + dt * 16 + 4 * g);
;       uint2 w; w.x = pack2(pv[0] + o[qs][dt][0] * inv, pv[1] + o[qs][dt][1] * inv); w.y = pack2(pv[2] + o[qs][dt][2] * inv, pv[3] + o[qs][dt][3] * inv);
;       *(uint2*)(op + dt * 16 + 4 * g) = w;
	global_store_dwordx2 v[76:77], v[34:35], off offset:96
	s_waitcnt vmcnt(7)
	v_fma_f32 v124, v38, v0, v124
	v_fma_f32 v125, v39, v0, v125

; DI unsigned pack2(float lo, float hi) { unsigned r; asm("v_cvt_pk_bf16_f32 %0, %1, %2" : "=v"(r) : "v"(lo), "v"(hi)); return r; }
; template <int QS>
; DI void nsa_sel_item(int item, const bf16_t* __restrict__ z, const unsigned* __restrict__ sel, const float* __restrict__ bgate,
;                              const float* __restrict__ part, bf16_t* __restrict__ mix, char* smem) {
;     ...
;     for (int dt = 0; dt < 8; ++dt) {
;       const f32x4 pv = *(const f32x4*)(pp + dt * 16 + 4 * g);
;       uint2 w; w.x = pack2(pv[0] + o[qs][dt][0] * inv, pv[1] + o[qs][dt][1] * inv); w.y = pack2(pv[2] + o[qs][dt][2] * inv, pv[3] + o[qs][dt][3] * inv);
;       *(uint2*)(op + dt * 16 + 4 * g) = w;
	v_cvt_pk_bf16_f32 v124, v124, v125

; DI unsigned pack2(float lo, float hi) { unsigned r; asm("v_cvt_pk_bf16_f32 %0, %1, %2" : "=v"(r) : "v"(lo), "v"(hi)); return r; }
; template <int QS>
; DI void nsa_sel_item(int item, const bf16_t* __restrict__ z, const unsigned* __restrict__ sel, const float* __restrict__ bgate,
;                              const float* __restrict__ part, bf16_t* __restrict__ mix, char* smem) {
;     ...
;     for (int dt = 0; dt < 8; ++dt) {
;       const f32x4 pv = *(const f32x4*)(pp + dt * 16 + 4 * g);
;       uint2 w; w.x = pack2(pv[0] + o[qs][dt][0] * inv, pv[1] + o[qs][dt][1] * inv); w.y = pack2(pv[2] + o[qs][dt][2] * inv, pv[3] + o[qs][dt][3] * inv);
;       *(uint2*)(op + dt * 16 + 4 * g) = w;
	v_fma_f32 v125, v40, v0, v126
	v_fmac_f32_e32 v127, v41, v0

; DI unsigned pack2(float lo, float hi) { unsigned r; asm("v_cvt_pk_bf16_f32 %0, %1, %2" : "=v"(r) : "v"(lo), "v"(hi)); return r; }
; template <int QS>
; DI void nsa_sel_item(int item, const bf16_t* __restrict__ z, const unsigned* __restrict__ sel, const float* __restrict__ bgate,
;                              const float* __restrict__ part, bf16_t* __restrict__ mix, char* smem) {
;     ...
;     for (int dt = 0; dt < 8; ++dt) {
;       const f32x4 pv = *(const f32x4*)(pp + dt * 16 + 4 * g);
;       uint2 w; w.x = pack2(pv[0] + o[qs][dt][0] * inv, pv[1] + o[qs][dt][1] * inv); w.y = pack2(pv[2] + o[qs][dt][2] * inv, pv[3] + o[qs][dt][3] * inv);
;       *(uint2*)(op + dt * 16 + 4 * g) = w;
	v_cvt_pk_bf16_f32 v125, v125, v127

; DI unsigned pack2(float lo, float hi) { unsigned r; asm("v_cvt_pk_bf16_f32 %0, %1, %2" : "=v"(r) : "v"(lo), "v"(hi)); return r; }
; template <int QS>
; DI void nsa_sel_item(int item, const bf16_t* __restrict__ z, const unsigned* __restrict__ sel, const float* __restrict__ bgate,
;                              const float* __restrict__ part, bf16_t* __restrict__ mix, char* smem) {
;     ...
;     for (int dt = 0; dt < 8; ++dt) {
;       const f32x4 pv = *(const f32x4*)(pp + dt * 16 + 4 * g);
;       uint2 w; w.x = pack2(pv[0] + o[qs][dt][0] * inv, pv[1] + o[qs][dt][1] * inv); w.y = pack2(pv[2] + o[qs][dt][2] * inv, pv[3] + o[qs][dt][3] * inv);
;       *(uint2*)(op + dt * 16 + 4 * g) = w;
	global_store_dwordx2 v[76:77], v[124:125], off offset:128
	s_waitcnt vmcnt(7)
	v_fma_f32 v132, v50, v0, v132
	v_fma_f32 v133, v51, v0, v133

; DI unsigned pack2(float lo, float hi) { unsigned r; asm("v_cvt_pk_bf16_f32 %0, %1, %2" : "=v"(r) : "v"(lo), "v"(hi)); return r; }
; template <int QS>
; DI void nsa_sel_item(int item, const bf16_t* __restrict__ z, const unsigned* __restrict__ sel, const float* __restrict__ bgate,
;                              const float* __restrict__ part, bf16_t* __restrict__ mix, char* smem) {
;     ...
;     for (int dt = 0; dt < 8; ++dt) {
;       const f32x4 pv = *(const f32x4*)(pp + dt * 16 + 4 * g);
;       uint2 w; w.x = pack2(pv[0] + o[qs][dt][0] * inv, pv[1] + o[qs][dt][1] * inv); w.y = pack2(pv[2] + o[qs][dt][2] * inv, pv[3] + o[qs][dt][3] * inv);
;       *(uint2*)(op + dt * 16 + 4 * g) = w;
	v_cvt_pk_bf16_f32 v132, v132, v133

; DI unsigned pack2(float lo, float hi) { unsigned r; asm("v_cvt_pk_bf16_f32 %0, %1, %2" : "=v"(r) : "v"(lo), "v"(hi)); return r; }
; template <int QS>
; DI void nsa_sel_item(int item, const bf16_t* __restrict__ z, const unsigned* __restrict__ sel, const float* __restrict__ bgate,
;                              const float* __restrict__ part, bf16_t* __restrict__ mix, char* smem) {
;     ...
;     for (int dt = 0; dt < 8; ++dt) {
;       const f32x4 pv = *(const f32x4*)(pp + dt * 16 + 4 * g);
;       uint2 w; w.x = pack2(pv[0] + o[qs][dt][0] * inv, pv[1] + o[qs][dt][1] * inv); w.y = pack2(pv[2] + o[qs][dt][2] * inv, pv[3] + o[qs][dt][3] * inv);
;       *(uint2*)(op + dt * 16 + 4 * g) = w;
	v_fma_f32 v133, v52, v0, v134
	v_fmac_f32_e32 v135, v53, v0

; DI unsigned pack2(float lo, float hi) { unsigned r; asm("v_cvt_pk_bf16_f32 %0, %1, %2" : "=v"(r) : "v"(lo), "v"(hi)); return r; }
; template <int QS>
; DI void nsa_sel_item(int item, const bf16_t* __restrict__ z, const unsigned* __restrict__ sel, const float* __restrict__ bgate,
;                              const float* __restrict__ part, bf16_t* __restrict__ mix, char* smem) {
;     ...
;     for (int dt = 0; dt < 8; ++dt) {
;       const f32x4 pv = *(const f32x4*)(pp + dt * 16 + 4 * g);
;       uint2 w; w.x = pack2(pv[0] + o[qs][dt][0] * inv, pv[1] + o[qs][dt][1] * inv); w.y = pack2(pv[2] + o[qs][dt][2] * inv, pv[3] + o[qs][dt][3] * inv);
;       *(uint2*)(op + dt * 16 + 4 * g) = w;
	v_cvt_pk_bf16_f32 v133, v133, v135

; DI unsigned pack2(float lo, float hi) { unsigned r; asm("v_cvt_pk_bf16_f32 %0, %1, %2" : "=v"(r) : "v"(lo), "v"(hi)); return r; }
; template <int QS>
; DI void nsa_sel_item(int item, const bf16_t* __restrict__ z, const unsigned* __restrict__ sel, const float* __restrict__ bgate,
;                              const float* __restrict__ part, bf16_t* __restrict__ mix, char* smem) {
;     ...
;     for (int dt = 0; dt < 8; ++dt) {
;       const f32x4 pv = *(const f32x4*)(pp + dt * 16 + 4 * g);
;       uint2 w; w.x = pack2(pv[0] + o[qs][dt][0] * inv, pv[1] + o[qs][dt][1] * inv); w.y = pack2(pv[2] + o[qs][dt][2] * inv, pv[3] + o[qs][dt][3] * inv);
;       *(uint2*)(op + dt * 16 + 4 * g) = w;
	global_store_dwordx2 v[76:77], v[132:133], off offset:160
	s_waitcnt vmcnt(7)
	v_fma_f32 v136, v58, v0, v136
	v_fma_f32 v137, v59, v0, v137

; DI unsigned pack2(float lo, float hi) { unsigned r; asm("v_cvt_pk_bf16_f32 %0, %1, %2" : "=v"(r) : "v"(lo), "v"(hi)); return r; }
; template <int QS>
; DI void nsa_sel_item(int item, const bf16_t* __restrict__ z, const unsigned* __restrict__ sel, const float* __restrict__ bgate,
;                              const float* __restrict__ part, bf16_t* __restrict__ mix, char* smem) {
;     ...
;     for (int dt = 0; dt < 8; ++dt) {
;       const f32x4 pv = *(const f32x4*)(pp + dt * 16 + 4 * g);
;       uint2 w; w.x = pack2(pv[0] + o[qs][dt][0] * inv, pv[1] + o[qs][dt][1] * inv); w.y = pack2(pv[2] + o[qs][dt][2] * inv, pv[3] + o[qs][dt][3] * inv);
;       *(uint2*)(op + dt * 16 + 4 * g) = w;
	v_cvt_pk_bf16_f32 v136, v136, v137

; DI unsigned pack2(float lo, float hi) { unsigned r; asm("v_cvt_pk_bf16_f32 %0, %1, %2" : "=v"(r) : "v"(lo), "v"(hi)); return r; }
; template <int QS>
; DI void nsa_sel_item(int item, const bf16_t* __restrict__ z, const unsigned* __restrict__ sel, const float* __restrict__ bgate,
;                              const float* __restrict__ part, bf16_t* __restrict__ mix, char* smem) {
;     ...
;     for (int dt = 0; dt < 8; ++dt) {
;       const f32x4 pv = *(const f32x4*)(pp + dt * 16 + 4 * g);
;       uint2 w; w.x = pack2(pv[0] + o[qs][dt][0] * inv, pv[1] + o[qs][dt][1] * inv); w.y = pack2(pv[2] + o[qs][dt][2] * inv, pv[3] + o[qs][dt][3] * inv);
;       *(uint2*)(op + dt * 16 + 4 * g) = w;
	v_fma_f32 v137, v60, v0, v138
	v_fmac_f32_e32 v139, v61, v0

; DI unsigned pack2(float lo, float hi) { unsigned r; asm("v_cvt_pk_bf16_f32 %0, %1, %2" : "=v"(r) : "v"(lo), "v"(hi)); return r; }
; template <int QS>
; DI void nsa_sel_item(int item, const bf16_t* __restrict__ z, const unsigned* __restrict__ sel, const float* __restrict__ bgate,
;                              const float* __restrict__ part, bf16_t* __restrict__ mix, char* smem) {
;     ...
;     for (int dt = 0; dt < 8; ++dt) {
;       const f32x4 pv = *(const f32x4*)(pp + dt * 16 + 4 * g);
;       uint2 w; w.x = pack2(pv[0] + o[qs][dt][0] * inv, pv[1] + o[qs][dt][1] * inv); w.y = pack2(pv[2] + o[qs][dt][2] * inv, pv[3] + o[qs][dt][3] * inv);
;       *(uint2*)(op + dt * 16 + 4 * g) = w;
	v_cvt_pk_bf16_f32 v137, v137, v139

; DI unsigned pack2(float lo, float hi) { unsigned r; asm("v_cvt_pk_bf16_f32 %0, %1, %2" : "=v"(r) : "v"(lo), "v"(hi)); return r; }
; template <int QS>
; DI void nsa_sel_item(int item, const bf16_t* __restrict__ z, const unsigned* __restrict__ sel, const float* __restrict__ bgate,
;                              const float* __restrict__ part, bf16_t* __restrict__ mix, char* smem) {
;     ...
;     for (int dt = 0; dt < 8; ++dt) {
;       const f32x4 pv = *(const f32x4*)(pp + dt * 16 + 4 * g);
;       uint2 w; w.x = pack2(pv[0] + o[qs][dt][0] * inv, pv[1] + o[qs][dt][1] * inv); w.y = pack2(pv[2] + o[qs][dt][2] * inv, pv[3] + o[qs][dt][3] * inv);
;       *(uint2*)(op + dt * 16 + 4 * g) = w;
	global_store_dwordx2 v[76:77], v[136:137], off offset:192
	s_waitcnt vmcnt(7)
	v_fma_f32 v140, v94, v0, v140
	v_fma_f32 v141, v95, v0, v141

; DI unsigned pack2(float lo, float hi) { unsigned r; asm("v_cvt_pk_bf16_f32 %0, %1, %2" : "=v"(r) : "v"(lo), "v"(hi)); return r; }
; template <int QS>
; DI void nsa_sel_item(int item, const bf16_t* __restrict__ z, const unsigned* __restrict__ sel, const float* __restrict__ bgate,
;                              const float* __restrict__ part, bf16_t* __restrict__ mix, char* smem) {
;     ...
;     for (int dt = 0; dt < 8; ++dt) {
;       const f32x4 pv = *(const f32x4*)(pp + dt * 16 + 4 * g);
;       uint2 w; w.x = pack2(pv[0] + o[qs][dt][0] * inv, pv[1] + o[qs][dt][1] * inv); w.y = pack2(pv[2] + o[qs][dt][2] * inv, pv[3] + o[qs][dt][3] * inv);
;       *(uint2*)(op + dt * 16 + 4 * g) = w;
	v_cvt_pk_bf16_f32 v140, v140, v141

; DI unsigned pack2(float lo, float hi) { unsigned r; asm("v_cvt_pk_bf16_f32 %0, %1, %2" : "=v"(r) : "v"(lo), "v"(hi)); return r; }
; template <int QS>
; DI void nsa_sel_item(int item, const bf16_t* __restrict__ z, const unsigned* __restrict__ sel, const float* __restrict__ bgate,
;                              const float* __restrict__ part, bf16_t* __restrict__ mix, char* smem) {
;     ...
;     float lt = l[qs]; lt += __shfl_xor(lt, 16); lt += __shfl_xor(lt, 32);
;     ...
;     for (int dt = 0; dt < 8; ++dt) {
;       const f32x4 pv = *(const f32x4*)(pp + dt * 16 + 4 * g);
;       uint2 w; w.x = pack2(pv[0] + o[qs][dt][0] * inv, pv[1] + o[qs][dt][1] * inv); w.y = pack2(pv[2] + o[qs][dt][2] * inv, pv[3] + o[qs][dt][3] * inv);
;       *(uint2*)(op + dt * 16 + 4 * g) = w;
	v_fma_f32 v141, v96, v0, v142
	v_fmac_f32_e32 v143, v97, v0
	ds_bpermute_b32 v0, v69, v106

; DI unsigned pack2(float lo, float hi) { unsigned r; asm("v_cvt_pk_bf16_f32 %0, %1, %2" : "=v"(r) : "v"(lo), "v"(hi)); return r; }
; template <int QS>
; DI void nsa_sel_item(int item, const bf16_t* __restrict__ z, const unsigned* __restrict__ sel, const float* __restrict__ bgate,
;                              const float* __restrict__ part, bf16_t* __restrict__ mix, char* smem) {
;     ...
;     for (int dt = 0; dt < 8; ++dt) {
;       const f32x4 pv = *(const f32x4*)(pp + dt * 16 + 4 * g);
;       uint2 w; w.x = pack2(pv[0] + o[qs][dt][0] * inv, pv[1] + o[qs][dt][1] * inv); w.y = pack2(pv[2] + o[qs][dt][2] * inv, pv[3] + o[qs][dt][3] * inv);
;       *(uint2*)(op + dt * 16 + 4 * g) = w;
	v_cvt_pk_bf16_f32 v141, v141, v143

; DI unsigned pack2(float lo, float hi) { unsigned r; asm("v_cvt_pk_bf16_f32 %0, %1, %2" : "=v"(r) : "v"(lo), "v"(hi)); return r; }
; template <int QS>
; DI void nsa_sel_item(int item, const bf16_t* __restrict__ z, const unsigned* __restrict__ sel, const float* __restrict__ bgate,
;                              const float* __restrict__ part, bf16_t* __restrict__ mix, char* smem) {
;     ...
;     float lt = l[qs]; lt += __shfl_xor(lt, 16); lt += __shfl_xor(lt, 32);
;     const float inv = (lt > 0.f ? 1.f / lt : 0.f) * nsa_gate(z, bgate, tb + qi[qs], hh, 1);
;     const float* pp = part + (tb + qi[qs]) * DM + hh * 128;
;     bf16_t* op = mix + (tb + qi[qs]) * DM + hh * 128;
; #pragma unroll
;     for (int dt = 0; dt < 8; ++dt) {
;       const f32x4 pv = *(const f32x4*)(pp + dt * 16 + 4 * g);
;       uint2 w; w.x = pack2(pv[0] + o[qs][dt][0] * inv, pv[1] + o[qs][dt][1] * inv); w.y = pack2(pv[2] + o[qs][dt][2] * inv, pv[3] + o[qs][dt][3] * inv);
;       *(uint2*)(op + dt * 16 + 4 * g) = w;
	global_store_dwordx2 v[76:77], v[140:141], off offset:224
	s_waitcnt lgkmcnt(0)
	v_add_f32_e32 v0, v106, v0
	ds_bpermute_b32 v34, v78, v0
	s_waitcnt lgkmcnt(0)
	v_add_f32_e32 v0, v0, v34
	v_div_scale_f32 v34, s[4:5], v0, v0, 1.0
	v_rcp_f32_e32 v35, v34
	v_cmp_lt_f32_e64 s[0:1], 0, v0
	v_fma_f32 v36, -v34, v35, 1.0
	v_fmac_f32_e32 v35, v36, v35
	v_div_scale_f32 v36, vcc, 1.0, v0, 1.0
	v_mul_f32_e32 v37, v36, v35
	v_fma_f32 v38, -v34, v37, v36
	v_fmac_f32_e32 v37, v38, v35
	v_fma_f32 v34, -v34, v37, v36
	v_div_fmas_f32 v34, v34, v35, v37
	v_div_fixup_f32 v0, v34, v0, 1.0
	v_lshl_add_u64 v[34:35], s[2:3], 0, v[66:67]
	v_add_co_u32_e32 v34, vcc, s93, v34
	v_cndmask_b32_e64 v0, 0, v0, s[0:1]
	s_nop 0
	v_addc_co_u32_e32 v35, vcc, 0, v35, vcc
	global_load_ushort v34, v[34:35], off offset:2050
	s_waitcnt vmcnt(0)
	v_lshlrev_b32_e32 v34, 16, v34
	v_add_f32_e32 v34, v68, v34
	v_mul_f32_e32 v34, 0xbfb8aa3b, v34
	v_exp_f32_e32 v34, v34
	s_nop 0
	v_add_f32_e32 v34, 1.0, v34
	v_div_scale_f32 v35, s[0:1], v34, v34, 1.0
	v_rcp_f32_e32 v36, v35
	s_nop 0
	v_fma_f32 v37, -v35, v36, 1.0
	v_fmac_f32_e32 v36, v37, v36
	v_div_scale_f32 v37, vcc, 1.0, v34, 1.0
	v_mul_f32_e32 v38, v37, v36
	v_fma_f32 v39, -v35, v38, v37
	v_fmac_f32_e32 v38, v39, v36
	v_fma_f32 v35, -v35, v38, v37
	v_div_fmas_f32 v35, v35, v36, v38
	v_div_fixup_f32 v34, v35, v34, 1.0
	v_mul_f32_e32 v0, v0, v34
	v_lshlrev_b64 v[34:35], 13, v[130:131]
	v_lshl_add_u64 v[36:37], v[62:63], 0, v[34:35]
	global_load_dwordx4 v[108:111], v[36:37], off
	global_load_dwordx4 v[112:115], v[36:37], off offset:64
	global_load_dwordx4 v[116:119], v[36:37], off offset:128
	global_load_dwordx4 v[120:123], v[36:37], off offset:192
	global_load_dwordx4 v[124:127], v[36:37], off offset:256
	global_load_dwordx4 v[132:135], v[36:37], off offset:320
	global_load_dwordx4 v[136:139], v[36:37], off offset:384
	global_load_dwordx4 v[140:143], v[36:37], off offset:448
	v_lshlrev_b64 v[34:35], 12, v[130:131]
	v_lshl_add_u64 v[34:35], v[64:65], 0, v[34:35]
	s_waitcnt vmcnt(7)
	v_fma_f32 v30, v30, v0, v108
	v_fma_f32 v31, v31, v0, v109

; DI unsigned pack2(float lo, float hi) { unsigned r; asm("v_cvt_pk_bf16_f32 %0, %1, %2" : "=v"(r) : "v"(lo), "v"(hi)); return r; }
; template <int QS>
; DI void nsa_sel_item(int item, const bf16_t* __restrict__ z, const unsigned* __restrict__ sel, const float* __restrict__ bgate,
;                              const float* __restrict__ part, bf16_t* __restrict__ mix, char* smem) {
;     ...
;     for (int dt = 0; dt < 8; ++dt) {
;       const f32x4 pv = *(const f32x4*)(pp + dt * 16 + 4 * g);
;       uint2 w; w.x = pack2(pv[0] + o[qs][dt][0] * inv, pv[1] + o[qs][dt][1] * inv); w.y = pack2(pv[2] + o[qs][dt][2] * inv, pv[3] + o[qs][dt][3] * inv);
;       *(uint2*)(op + dt * 16 + 4 * g) = w;
	v_cvt_pk_bf16_f32 v30, v30, v31

; DI unsigned pack2(float lo, float hi) { unsigned r; asm("v_cvt_pk_bf16_f32 %0, %1, %2" : "=v"(r) : "v"(lo), "v"(hi)); return r; }
; template <int QS>
; DI void nsa_sel_item(int item, const bf16_t* __restrict__ z, const unsigned* __restrict__ sel, const float* __restrict__ bgate,
;                              const float* __restrict__ part, bf16_t* __restrict__ mix, char* smem) {
;     ...
;     for (int dt = 0; dt < 8; ++dt) {
;       const f32x4 pv = *(const f32x4*)(pp + dt * 16 + 4 * g);
;       uint2 w; w.x = pack2(pv[0] + o[qs][dt][0] * inv, pv[1] + o[qs][dt][1] * inv); w.y = pack2(pv[2] + o[qs][dt][2] * inv, pv[3] + o[qs][dt][3] * inv);
;       *(uint2*)(op + dt * 16 + 4 * g) = w;
	v_fma_f32 v31, v32, v0, v110
	v_fmac_f32_e32 v111, v33, v0

; DI unsigned pack2(float lo, float hi) { unsigned r; asm("v_cvt_pk_bf16_f32 %0, %1, %2" : "=v"(r) : "v"(lo), "v"(hi)); return r; }
; template <int QS>
; DI void nsa_sel_item(int item, const bf16_t* __restrict__ z, const unsigned* __restrict__ sel, const float* __restrict__ bgate,
;                              const float* __restrict__ part, bf16_t* __restrict__ mix, char* smem) {
;     ...
;     for (int dt = 0; dt < 8; ++dt) {
;       const f32x4 pv = *(const f32x4*)(pp + dt * 16 + 4 * g);
;       uint2 w; w.x = pack2(pv[0] + o[qs][dt][0] * inv, pv[1] + o[qs][dt][1] * inv); w.y = pack2(pv[2] + o[qs][dt][2] * inv, pv[3] + o[qs][dt][3] * inv);
;       *(uint2*)(op + dt * 16 + 4 * g) = w;
	v_cvt_pk_bf16_f32 v31, v31, v111

; DI unsigned pack2(float lo, float hi) { unsigned r; asm("v_cvt_pk_bf16_f32 %0, %1, %2" : "=v"(r) : "v"(lo), "v"(hi)); return r; }
; template <int QS>
; DI void nsa_sel_item(int item, const bf16_t* __restrict__ z, const unsigned* __restrict__ sel, const float* __restrict__ bgate,
;                              const float* __restrict__ part, bf16_t* __restrict__ mix, char* smem) {
;     ...
;     for (int dt = 0; dt < 8; ++dt) {
;       const f32x4 pv = *(const f32x4*)(pp + dt * 16 + 4 * g);
;       uint2 w; w.x = pack2(pv[0] + o[qs][dt][0] * inv, pv[1] + o[qs][dt][1] * inv); w.y = pack2(pv[2] + o[qs][dt][2] * inv, pv[3] + o[qs][dt][3] * inv);
;       *(uint2*)(op + dt * 16 + 4 * g) = w;
	global_store_dwordx2 v[34:35], v[30:31], off
	s_waitcnt vmcnt(7)
	v_fma_f32 v26, v26, v0, v112
	v_fma_f32 v27, v27, v0, v113

; DI unsigned pack2(float lo, float hi) { unsigned r; asm("v_cvt_pk_bf16_f32 %0, %1, %2" : "=v"(r) : "v"(lo), "v"(hi)); return r; }
; template <int QS>
; DI void nsa_sel_item(int item, const bf16_t* __restrict__ z, const unsigned* __restrict__ sel, const float* __restrict__ bgate,
;                              const float* __restrict__ part, bf16_t* __restrict__ mix, char* smem) {
;     ...
;     for (int dt = 0; dt < 8; ++dt) {
;       const f32x4 pv = *(const f32x4*)(pp + dt * 16 + 4 * g);
;       uint2 w; w.x = pack2(pv[0] + o[qs][dt][0] * inv, pv[1] + o[qs][dt][1] * inv); w.y = pack2(pv[2] + o[qs][dt][2] * inv, pv[3] + o[qs][dt][3] * inv);
;       *(uint2*)(op + dt * 16 + 4 * g) = w;
	v_cvt_pk_bf16_f32 v26, v26, v27

; DI unsigned pack2(float lo, float hi) { unsigned r; asm("v_cvt_pk_bf16_f32 %0, %1, %2" : "=v"(r) : "v"(lo), "v"(hi)); return r; }
; template <int QS>
; DI void nsa_sel_item(int item, const bf16_t* __restrict__ z, const unsigned* __restrict__ sel, const float* __restrict__ bgate,
;                              const float* __restrict__ part, bf16_t* __restrict__ mix, char* smem) {
;     ...
;     for (int dt = 0; dt < 8; ++dt) {
;       const f32x4 pv = *(const f32x4*)(pp + dt * 16 + 4 * g);
;       uint2 w; w.x = pack2(pv[0] + o[qs][dt][0] * inv, pv[1] + o[qs][dt][1] * inv); w.y = pack2(pv[2] + o[qs][dt][2] * inv, pv[3] + o[qs][dt][3] * inv);
;       *(uint2*)(op + dt * 16 + 4 * g) = w;
	v_fma_f32 v27, v28, v0, v114
	v_fmac_f32_e32 v115, v29, v0

; DI unsigned pack2(float lo, float hi) { unsigned r; asm("v_cvt_pk_bf16_f32 %0, %1, %2" : "=v"(r) : "v"(lo), "v"(hi)); return r; }
; template <int QS>
; DI void nsa_sel_item(int item, const bf16_t* __restrict__ z, const unsigned* __restrict__ sel, const float* __restrict__ bgate,
;                              const float* __restrict__ part, bf16_t* __restrict__ mix, char* smem) {
;     ...
;     for (int dt = 0; dt < 8; ++dt) {
;       const f32x4 pv = *(const f32x4*)(pp + dt * 16 + 4 * g);
;       uint2 w; w.x = pack2(pv[0] + o[qs][dt][0] * inv, pv[1] + o[qs][dt][1] * inv); w.y = pack2(pv[2] + o[qs][dt][2] * inv, pv[3] + o[qs][dt][3] * inv);
;       *(uint2*)(op + dt * 16 + 4 * g) = w;
	v_cvt_pk_bf16_f32 v27, v27, v115

; DI unsigned pack2(float lo, float hi) { unsigned r; asm("v_cvt_pk_bf16_f32 %0, %1, %2" : "=v"(r) : "v"(lo), "v"(hi)); return r; }
; template <int QS>
; DI void nsa_sel_item(int item, const bf16_t* __restrict__ z, const unsigned* __restrict__ sel, const float* __restrict__ bgate,
;                              const float* __restrict__ part, bf16_t* __restrict__ mix, char* smem) {
;     ...
;     for (int dt = 0; dt < 8; ++dt) {
;       const f32x4 pv = *(const f32x4*)(pp + dt * 16 + 4 * g);
;       uint2 w; w.x = pack2(pv[0] + o[qs][dt][0] * inv, pv[1] + o[qs][dt][1] * inv); w.y = pack2(pv[2] + o[qs][dt][2] * inv, pv[3] + o[qs][dt][3] * inv);
;       *(uint2*)(op + dt * 16 + 4 * g) = w;
	global_store_dwordx2 v[34:35], v[26:27], off offset:32
	s_waitcnt vmcnt(7)
	v_fma_f32 v22, v22, v0, v116
	v_fma_f32 v23, v23, v0, v117

; DI unsigned pack2(float lo, float hi) { unsigned r; asm("v_cvt_pk_bf16_f32 %0, %1, %2" : "=v"(r) : "v"(lo), "v"(hi)); return r; }
; template <int QS>
; DI void nsa_sel_item(int item, const bf16_t* __restrict__ z, const unsigned* __restrict__ sel, const float* __restrict__ bgate,
;                              const float* __restrict__ part, bf16_t* __restrict__ mix, char* smem) {
;     ...
;     for (int dt = 0; dt < 8; ++dt) {
;       const f32x4 pv = *(const f32x4*)(pp + dt * 16 + 4 * g);
;       uint2 w; w.x = pack2(pv[0] + o[qs][dt][0] * inv, pv[1] + o[qs][dt][1] * inv); w.y = pack2(pv[2] + o[qs][dt][2] * inv, pv[3] + o[qs][dt][3] * inv);
;       *(uint2*)(op + dt * 16 + 4 * g) = w;
	v_cvt_pk_bf16_f32 v22, v22, v23

; DI unsigned pack2(float lo, float hi) { unsigned r; asm("v_cvt_pk_bf16_f32 %0, %1, %2" : "=v"(r) : "v"(lo), "v"(hi)); return r; }
; template <int QS>
; DI void nsa_sel_item(int item, const bf16_t* __restrict__ z, const unsigned* __restrict__ sel, const float* __restrict__ bgate,
;                              const float* __restrict__ part, bf16_t* __restrict__ mix, char* smem) {
;     ...
;     for (int dt = 0; dt < 8; ++dt) {
;       const f32x4 pv = *(const f32x4*)(pp + dt * 16 + 4 * g);
;       uint2 w; w.x = pack2(pv[0] + o[qs][dt][0] * inv, pv[1] + o[qs][dt][1] * inv); w.y = pack2(pv[2] + o[qs][dt][2] * inv, pv[3] + o[qs][dt][3] * inv);
;       *(uint2*)(op + dt * 16 + 4 * g) = w;
	v_fma_f32 v23, v24, v0, v118
	v_fmac_f32_e32 v119, v25, v0

; DI unsigned pack2(float lo, float hi) { unsigned r; asm("v_cvt_pk_bf16_f32 %0, %1, %2" : "=v"(r) : "v"(lo), "v"(hi)); return r; }
; template <int QS>
; DI void nsa_sel_item(int item, const bf16_t* __restrict__ z, const unsigned* __restrict__ sel, const float* __restrict__ bgate,
;                              const float* __restrict__ part, bf16_t* __restrict__ mix, char* smem) {
;     ...
;     for (int dt = 0; dt < 8; ++dt) {
;       const f32x4 pv = *(const f32x4*)(pp + dt * 16 + 4 * g);
;       uint2 w; w.x = pack2(pv[0] + o[qs][dt][0] * inv, pv[1] + o[qs][dt][1] * inv); w.y = pack2(pv[2] + o[qs][dt][2] * inv, pv[3] + o[qs][dt][3] * inv);
;       *(uint2*)(op + dt * 16 + 4 * g) = w;
	v_cvt_pk_bf16_f32 v23, v23, v119

; DI unsigned pack2(float lo, float hi) { unsigned r; asm("v_cvt_pk_bf16_f32 %0, %1, %2" : "=v"(r) : "v"(lo), "v"(hi)); return r; }
; template <int QS>
; DI void nsa_sel_item(int item, const bf16_t* __restrict__ z, const unsigned* __restrict__ sel, const float* __restrict__ bgate,
;                              const float* __restrict__ part, bf16_t* __restrict__ mix, char* smem) {
;     ...
;     for (int dt = 0; dt < 8; ++dt) {
;       const f32x4 pv = *(const f32x4*)(pp + dt * 16 + 4 * g);
;       uint2 w; w.x = pack2(pv[0] + o[qs][dt][0] * inv, pv[1] + o[qs][dt][1] * inv); w.y = pack2(pv[2] + o[qs][dt][2] * inv, pv[3] + o[qs][dt][3] * inv);
;       *(uint2*)(op + dt * 16 + 4 * g) = w;
	global_store_dwordx2 v[34:35], v[22:23], off offset:64
	s_waitcnt vmcnt(7)
	v_fma_f32 v18, v18, v0, v120
	v_fma_f32 v19, v19, v0, v121

; DI unsigned pack2(float lo, float hi) { unsigned r; asm("v_cvt_pk_bf16_f32 %0, %1, %2" : "=v"(r) : "v"(lo), "v"(hi)); return r; }
; template <int QS>
; DI void nsa_sel_item(int item, const bf16_t* __restrict__ z, const unsigned* __restrict__ sel, const float* __restrict__ bgate,
;                              const float* __restrict__ part, bf16_t* __restrict__ mix, char* smem) {
;     ...
;     for (int dt = 0; dt < 8; ++dt) {
;       const f32x4 pv = *(const f32x4*)(pp + dt * 16 + 4 * g);
;       uint2 w; w.x = pack2(pv[0] + o[qs][dt][0] * inv, pv[1] + o[qs][dt][1] * inv); w.y = pack2(pv[2] + o[qs][dt][2] * inv, pv[3] + o[qs][dt][3] * inv);
;       *(uint2*)(op + dt * 16 + 4 * g) = w;
	v_cvt_pk_bf16_f32 v18, v18, v19

; DI unsigned pack2(float lo, float hi) { unsigned r; asm("v_cvt_pk_bf16_f32 %0, %1, %2" : "=v"(r) : "v"(lo), "v"(hi)); return r; }
; template <int QS>
; DI void nsa_sel_item(int item, const bf16_t* __restrict__ z, const unsigned* __restrict__ sel, const float* __restrict__ bgate,
;                              const float* __restrict__ part, bf16_t* __restrict__ mix, char* smem) {
;     ...
;     for (int dt = 0; dt < 8; ++dt) {
;       const f32x4 pv = *(const f32x4*)(pp + dt * 16 + 4 * g);
;       uint2 w; w.x = pack2(pv[0] + o[qs][dt][0] * inv, pv[1] + o[qs][dt][1] * inv); w.y = pack2(pv[2] + o[qs][dt][2] * inv, pv[3] + o[qs][dt][3] * inv);
;       *(uint2*)(op + dt * 16 + 4 * g) = w;
	v_fma_f32 v19, v20, v0, v122
	v_fmac_f32_e32 v123, v21, v0

; DI unsigned pack2(float lo, float hi) { unsigned r; asm("v_cvt_pk_bf16_f32 %0, %1, %2" : "=v"(r) : "v"(lo), "v"(hi)); return r; }
; template <int QS>
; DI void nsa_sel_item(int item, const bf16_t* __restrict__ z, const unsigned* __restrict__ sel, const float* __restrict__ bgate,
;                              const float* __restrict__ part, bf16_t* __restrict__ mix, char* smem) {
;     ...
;     for (int dt = 0; dt < 8; ++dt) {
;       const f32x4 pv = *(const f32x4*)(pp + dt * 16 + 4 * g);
;       uint2 w; w.x = pack2(pv[0] + o[qs][dt][0] * inv, pv[1] + o[qs][dt][1] * inv); w.y = pack2(pv[2] + o[qs][dt][2] * inv, pv[3] + o[qs][dt][3] * inv);
;       *(uint2*)(op + dt * 16 + 4 * g) = w;
	v_cvt_pk_bf16_f32 v19, v19, v123

; DI unsigned pack2(float lo, float hi) { unsigned r; asm("v_cvt_pk_bf16_f32 %0, %1, %2" : "=v"(r) : "v"(lo), "v"(hi)); return r; }
; template <int QS>
; DI void nsa_sel_item(int item, const bf16_t* __restrict__ z, const unsigned* __restrict__ sel, const float* __restrict__ bgate,
;                              const float* __restrict__ part, bf16_t* __restrict__ mix, char* smem) {
;     ...
;     for (int dt = 0; dt < 8; ++dt) {
;       const f32x4 pv = *(const f32x4*)(pp + dt * 16 + 4 * g);
;       uint2 w; w.x = pack2(pv[0] + o[qs][dt][0] * inv, pv[1] + o[qs][dt][1] * inv); w.y = pack2(pv[2] + o[qs][dt][2] * inv, pv[3] + o[qs][dt][3] * inv);
;       *(uint2*)(op + dt * 16 + 4 * g) = w;
	global_store_dwordx2 v[34:35], v[18:19], off offset:96
	s_waitcnt vmcnt(7)
	v_fma_f32 v14, v14, v0, v124
	v_fma_f32 v15, v15, v0, v125

; DI unsigned pack2(float lo, float hi) { unsigned r; asm("v_cvt_pk_bf16_f32 %0, %1, %2" : "=v"(r) : "v"(lo), "v"(hi)); return r; }
; template <int QS>
; DI void nsa_sel_item(int item, const bf16_t* __restrict__ z, const unsigned* __restrict__ sel, const float* __restrict__ bgate,
;                              const float* __restrict__ part, bf16_t* __restrict__ mix, char* smem) {
;     ...
;     for (int dt = 0; dt < 8; ++dt) {
;       const f32x4 pv = *(const f32x4*)(pp + dt * 16 + 4 * g);
;       uint2 w; w.x = pack2(pv[0] + o[qs][dt][0] * inv, pv[1] + o[qs][dt][1] * inv); w.y = pack2(pv[2] + o[qs][dt][2] * inv, pv[3] + o[qs][dt][3] * inv);
;       *(uint2*)(op + dt * 16 + 4 * g) = w;
	v_cvt_pk_bf16_f32 v14, v14, v15

; DI unsigned pack2(float lo, float hi) { unsigned r; asm("v_cvt_pk_bf16_f32 %0, %1, %2" : "=v"(r) : "v"(lo), "v"(hi)); return r; }
; template <int QS>
; DI void nsa_sel_item(int item, const bf16_t* __restrict__ z, const unsigned* __restrict__ sel, const float* __restrict__ bgate,
;                              const float* __restrict__ part, bf16_t* __restrict__ mix, char* smem) {
;     ...
;     for (int dt = 0; dt < 8; ++dt) {
;       const f32x4 pv = *(const f32x4*)(pp + dt * 16 + 4 * g);
;       uint2 w; w.x = pack2(pv[0] + o[qs][dt][0] * inv, pv[1] + o[qs][dt][1] * inv); w.y = pack2(pv[2] + o[qs][dt][2] * inv, pv[3] + o[qs][dt][3] * inv);
;       *(uint2*)(op + dt * 16 + 4 * g) = w;
	v_fma_f32 v15, v16, v0, v126
	v_fmac_f32_e32 v127, v17, v0

; DI unsigned pack2(float lo, float hi) { unsigned r; asm("v_cvt_pk_bf16_f32 %0, %1, %2" : "=v"(r) : "v"(lo), "v"(hi)); return r; }
; template <int QS>
; DI void nsa_sel_item(int item, const bf16_t* __restrict__ z, const unsigned* __restrict__ sel, const float* __restrict__ bgate,
;                              const float* __restrict__ part, bf16_t* __restrict__ mix, char* smem) {
;     ...
;       uint2 w; w.x = pack2(pv[0] + o[qs][dt][0] * inv, pv[1] + o[qs][dt][1] * inv); w.y = pack2(pv[2] + o[qs][dt][2] * inv, pv[3] + o[qs][dt][3] * inv);
	v_cvt_pk_bf16_f32 v15, v15, v127

; DI unsigned pack2(float lo, float hi) { unsigned r; asm("v_cvt_pk_bf16_f32 %0, %1, %2" : "=v"(r) : "v"(lo), "v"(hi)); return r; }
; template <int QS>
; DI void nsa_sel_item(int item, const bf16_t* __restrict__ z, const unsigned* __restrict__ sel, const float* __restrict__ bgate,
;                              const float* __restrict__ part, bf16_t* __restrict__ mix, char* smem) {
;     ...
;       const f32x4 pv = *(const f32x4*)(pp + dt * 16 + 4 * g);
;       uint2 w; w.x = pack2(pv[0] + o[qs][dt][0] * inv, pv[1] + o[qs][dt][1] * inv); w.y = pack2(pv[2] + o[qs][dt][2] * inv, pv[3] + o[qs][dt][3] * inv);
;       *(uint2*)(op + dt * 16 + 4 * g) = w;
	global_store_dwordx2 v[34:35], v[14:15], off offset:128
	s_waitcnt vmcnt(7)
	v_fma_f32 v10, v10, v0, v132
	v_fma_f32 v11, v11, v0, v133

; DI unsigned pack2(float lo, float hi) { unsigned r; asm("v_cvt_pk_bf16_f32 %0, %1, %2" : "=v"(r) : "v"(lo), "v"(hi)); return r; }
; template <int QS>
; DI void nsa_sel_item(int item, const bf16_t* __restrict__ z, const unsigned* __restrict__ sel, const float* __restrict__ bgate,
;                              const float* __restrict__ part, bf16_t* __restrict__ mix, char* smem) {
;     ...
;       uint2 w; w.x = pack2(pv[0] + o[qs][dt][0] * inv, pv[1] + o[qs][dt][1] * inv); w.y = pack2(pv[2] + o[qs][dt][2] * inv, pv[3] + o[qs][dt][3] * inv);
	v_cvt_pk_bf16_f32 v10, v10, v11

; DI unsigned pack2(float lo, float hi) { unsigned r; asm("v_cvt_pk_bf16_f32 %0, %1, %2" : "=v"(r) : "v"(lo), "v"(hi)); return r; }
; template <int QS>
; DI void nsa_sel_item(int item, const bf16_t* __restrict__ z, const unsigned* __restrict__ sel, const float* __restrict__ bgate,
;                              const float* __restrict__ part, bf16_t* __restrict__ mix, char* smem) {
;     ...
;       uint2 w; w.x = pack2(pv[0] + o[qs][dt][0] * inv, pv[1] + o[qs][dt][1] * inv); w.y = pack2(pv[2] + o[qs][dt][2] * inv, pv[3] + o[qs][dt][3] * inv);
	v_fma_f32 v11, v12, v0, v134
	v_fmac_f32_e32 v135, v13, v0

; DI unsigned pack2(float lo, float hi) { unsigned r; asm("v_cvt_pk_bf16_f32 %0, %1, %2" : "=v"(r) : "v"(lo), "v"(hi)); return r; }
; template <int QS>
; DI void nsa_sel_item(int item, const bf16_t* __restrict__ z, const unsigned* __restrict__ sel, const float* __restrict__ bgate,
;                              const float* __restrict__ part, bf16_t* __restrict__ mix, char* smem) {
;     ...
;       uint2 w; w.x = pack2(pv[0] + o[qs][dt][0] * inv, pv[1] + o[qs][dt][1] * inv); w.y = pack2(pv[2] + o[qs][dt][2] * inv, pv[3] + o[qs][dt][3] * inv);
	v_cvt_pk_bf16_f32 v11, v11, v135

; DI unsigned pack2(float lo, float hi) { unsigned r; asm("v_cvt_pk_bf16_f32 %0, %1, %2" : "=v"(r) : "v"(lo), "v"(hi)); return r; }
; template <int QS>
; DI void nsa_sel_item(int item, const bf16_t* __restrict__ z, const unsigned* __restrict__ sel, const float* __restrict__ bgate,
;                              const float* __restrict__ part, bf16_t* __restrict__ mix, char* smem) {
;     ...
;       const f32x4 pv = *(const f32x4*)(pp + dt * 16 + 4 * g);
;       uint2 w; w.x = pack2(pv[0] + o[qs][dt][0] * inv, pv[1] + o[qs][dt][1] * inv); w.y = pack2(pv[2] + o[qs][dt][2] * inv, pv[3] + o[qs][dt][3] * inv);
;       *(uint2*)(op + dt * 16 + 4 * g) = w;
	global_store_dwordx2 v[34:35], v[10:11], off offset:160
	s_waitcnt vmcnt(7)
	v_fma_f32 v6, v6, v0, v136
	v_fma_f32 v7, v7, v0, v137

; DI unsigned pack2(float lo, float hi) { unsigned r; asm("v_cvt_pk_bf16_f32 %0, %1, %2" : "=v"(r) : "v"(lo), "v"(hi)); return r; }
; template <int QS>
; DI void nsa_sel_item(int item, const bf16_t* __restrict__ z, const unsigned* __restrict__ sel, const float* __restrict__ bgate,
;                              const float* __restrict__ part, bf16_t* __restrict__ mix, char* smem) {
;     ...
;       uint2 w; w.x = pack2(pv[0] + o[qs][dt][0] * inv, pv[1] + o[qs][dt][1] * inv); w.y = pack2(pv[2] + o[qs][dt][2] * inv, pv[3] + o[qs][dt][3] * inv);
	v_cvt_pk_bf16_f32 v6, v6, v7

; DI unsigned pack2(float lo, float hi) { unsigned r; asm("v_cvt_pk_bf16_f32 %0, %1, %2" : "=v"(r) : "v"(lo), "v"(hi)); return r; }
; template <int QS>
; DI void nsa_sel_item(int item, const bf16_t* __restrict__ z, const unsigned* __restrict__ sel, const float* __restrict__ bgate,
;                              const float* __restrict__ part, bf16_t* __restrict__ mix, char* smem) {
;     ...
;       uint2 w; w.x = pack2(pv[0] + o[qs][dt][0] * inv, pv[1] + o[qs][dt][1] * inv); w.y = pack2(pv[2] + o[qs][dt][2] * inv, pv[3] + o[qs][dt][3] * inv);
	v_fma_f32 v7, v8, v0, v138
	v_fmac_f32_e32 v139, v9, v0

; DI unsigned pack2(float lo, float hi) { unsigned r; asm("v_cvt_pk_bf16_f32 %0, %1, %2" : "=v"(r) : "v"(lo), "v"(hi)); return r; }
; template <int QS>
; DI void nsa_sel_item(int item, const bf16_t* __restrict__ z, const unsigned* __restrict__ sel, const float* __restrict__ bgate,
;                              const float* __restrict__ part, bf16_t* __restrict__ mix, char* smem) {
;     ...
;       uint2 w; w.x = pack2(pv[0] + o[qs][dt][0] * inv, pv[1] + o[qs][dt][1] * inv); w.y = pack2(pv[2] + o[qs][dt][2] * inv, pv[3] + o[qs][dt][3] * inv);
	v_cvt_pk_bf16_f32 v7, v7, v139

; DI unsigned pack2(float lo, float hi) { unsigned r; asm("v_cvt_pk_bf16_f32 %0, %1, %2" : "=v"(r) : "v"(lo), "v"(hi)); return r; }
; template <int QS>
; DI void nsa_sel_item(int item, const bf16_t* __restrict__ z, const unsigned* __restrict__ sel, const float* __restrict__ bgate,
;                              const float* __restrict__ part, bf16_t* __restrict__ mix, char* smem) {
;     ...
;       const f32x4 pv = *(const f32x4*)(pp + dt * 16 + 4 * g);
;       uint2 w; w.x = pack2(pv[0] + o[qs][dt][0] * inv, pv[1] + o[qs][dt][1] * inv); w.y = pack2(pv[2] + o[qs][dt][2] * inv, pv[3] + o[qs][dt][3] * inv);
;       *(uint2*)(op + dt * 16 + 4 * g) = w;
	global_store_dwordx2 v[34:35], v[6:7], off offset:192
	s_waitcnt vmcnt(7)
	v_fma_f32 v2, v2, v0, v140
	v_fma_f32 v3, v3, v0, v141

; DI unsigned pack2(float lo, float hi) { unsigned r; asm("v_cvt_pk_bf16_f32 %0, %1, %2" : "=v"(r) : "v"(lo), "v"(hi)); return r; }
; template <int QS>
; DI void nsa_sel_item(int item, const bf16_t* __restrict__ z, const unsigned* __restrict__ sel, const float* __restrict__ bgate,
;                              const float* __restrict__ part, bf16_t* __restrict__ mix, char* smem) {
;     ...
;       uint2 w; w.x = pack2(pv[0] + o[qs][dt][0] * inv, pv[1] + o[qs][dt][1] * inv); w.y = pack2(pv[2] + o[qs][dt][2] * inv, pv[3] + o[qs][dt][3] * inv);
	v_cvt_pk_bf16_f32 v2, v2, v3

; DI unsigned pack2(float lo, float hi) { unsigned r; asm("v_cvt_pk_bf16_f32 %0, %1, %2" : "=v"(r) : "v"(lo), "v"(hi)); return r; }
; template <int QS>
; DI void nsa_sel_item(int item, const bf16_t* __restrict__ z, const unsigned* __restrict__ sel, const float* __restrict__ bgate,
;                              const float* __restrict__ part, bf16_t* __restrict__ mix, char* smem) {
;     ...
;       uint2 w; w.x = pack2(pv[0] + o[qs][dt][0] * inv, pv[1] + o[qs][dt][1] * inv); w.y = pack2(pv[2] + o[qs][dt][2] * inv, pv[3] + o[qs][dt][3] * inv);
	v_fma_f32 v3, v4, v0, v142
	v_fmac_f32_e32 v143, v5, v0

; DI unsigned pack2(float lo, float hi) { unsigned r; asm("v_cvt_pk_bf16_f32 %0, %1, %2" : "=v"(r) : "v"(lo), "v"(hi)); return r; }
; template <int QS>
; DI void nsa_sel_item(int item, const bf16_t* __restrict__ z, const unsigned* __restrict__ sel, const float* __restrict__ bgate,
;                              const float* __restrict__ part, bf16_t* __restrict__ mix, char* smem) {
;     ...
;       uint2 w; w.x = pack2(pv[0] + o[qs][dt][0] * inv, pv[1] + o[qs][dt][1] * inv); w.y = pack2(pv[2] + o[qs][dt][2] * inv, pv[3] + o[qs][dt][3] * inv);
	v_cvt_pk_bf16_f32 v3, v3, v143

; template <int QS>
; DI void nsa_sel_item(int item, const bf16_t* __restrict__ z, const unsigned* __restrict__ sel, const float* __restrict__ bgate,
;                              const float* __restrict__ part, bf16_t* __restrict__ mix, char* smem) {
;     ...
;       *(uint2*)(op + dt * 16 + 4 * g) = w;
	global_store_dwordx2 v[34:35], v[2:3], off offset:224
